# attention gen2 + mid-pipeline double barrier: next pair's first K fragments are read before the loop-back (no LDS latency behind the barrier)
# baseline (speedup 1.0000x reference)
.LBB0_1288:
	s_ashr_i32 s8, s6, 6
	s_and_b32 s9, s6, 63
	s_lshr_b32 s6, s42, 1
	s_add_i32 s20, s6, s30
	s_lshl_b32 s6, s42, 5
	s_and_b32 s6, s6, 32
	s_add_i32 s26, s6, s29
	s_and_b64 s[6:7], s[14:15], exec
	s_cselect_b32 s8, s20, s8
	s_cselect_b32 s6, s26, s9
	s_lshr_b32 s7, s8, 3
	s_mulk_i32 s7, 0x4100
	s_lshl_b32 s6, s6, 8
	s_and_b32 s9, s8, 7
	s_add_i32 s7, s7, s6
	v_add_u32_e32 v166, s7, v170
	s_lshl_b32 s20, s9, 7
	s_lshl_b32 s6, s9, 2
	s_mul_i32 s44, s8, 0x208000
	v_ashrrev_i32_e32 v167, 31, v166
	s_mul_hi_i32 s45, s8, 0x208000
	s_add_u32 s53, s31, s44
	v_lshlrev_b64 v[4:5], 5, v[166:167]
	s_addc_u32 s55, s34, s45
	s_mul_i32 s50, s8, 0x104000
	v_lshl_add_u64 v[4:5], s[12:13], 0, v[4:5]
	s_mov_b32 s7, s21
	s_mul_hi_i32 s51, s8, 0x104000
	s_add_u32 s62, s35, s50
	v_lshl_add_u64 v[4:5], v[4:5], 0, s[6:7]
	s_addc_u32 s63, s36, s51
	s_add_i32 s6, s8, 32
	v_lshlrev_b64 v[2:3], 10, v[166:167]
	s_ashr_i32 s7, s6, 31
	v_lshl_add_u64 v[2:3], s[16:17], 0, v[2:3]
	s_lshl_b64 s[6:7], s[6:7], 2
	v_lshl_add_u64 v[2:3], v[2:3], 0, s[20:21]
	s_add_u32 s6, s3, s6
	s_addc_u32 s7, s28, s7
	v_lshl_add_u64 v[2:3], v[2:3], 0, v[178:179]
	global_load_dword v58, v[4:5], off
	global_load_dword v50, v163, s[6:7]
	global_load_dwordx4 v[142:145], v[2:3], off offset:16
	global_load_dwordx4 v[138:141], v[2:3], off
	global_load_dwordx4 v[150:153], v[2:3], off offset:80
	global_load_dwordx4 v[146:149], v[2:3], off offset:64
	v_readfirstlane_b32 s6, v1
	s_ashr_i32 s26, s6, 6
	s_cmp_lt_i32 s26, 6
	s_mul_i32 s46, s26, 0xc00
	s_cselect_b64 s[8:9], -1, 0
	s_add_i32 s52, s46, 0xffffc000
	s_add_u32 s27, s62, s52
	s_addc_u32 s43, s63, 0
	s_ashr_i32 s47, s46, 31
	s_add_u32 s49, s53, s46
	s_addc_u32 s64, s55, s47
	s_and_b64 s[6:7], s[8:9], exec
	s_cselect_b32 s7, s64, s43
	s_cselect_b32 s6, s49, s27
	s_add_i32 s43, s46, 0
	s_cmp_lt_i32 s26, 5
	s_cselect_b64 s[26:27], -1, 0
	s_add_i32 s65, s46, 0x400
	s_ashr_i32 s66, s65, 31
	s_add_u32 s67, s49, 0x400
	s_addc_u32 s68, s64, 0
	s_add_i32 s48, s46, 0xffffc400
	s_add_u32 s69, s62, s48
	s_addc_u32 s70, s63, 0
	v_lshl_add_u64 v[2:3], s[6:7], 0, v[164:165]
	s_and_b64 s[6:7], s[26:27], exec
	s_mov_b32 m0, s43
	s_cselect_b32 s7, s68, s70
	s_cselect_b32 s6, s67, s69
	s_add_i32 s67, s46, 0x800
	v_lshrrev_b32 v154, 2, v0
	v_xor_b32 v154, v154, v0
	v_bfe_u32 v154, v154, 2, 1
	v_add_u32 v154, -1, v154
	v_and_b32 v154, 0x38383838, v154
	v_mov_b32 v155, v154
	v_mov_b32 v156, v154
	v_mov_b32 v157, v154
	v_mov_b32 v158, v154
	v_mov_b32 v159, v154
	v_mov_b32 v160, v154
	v_mov_b32 v161, v154
	global_load_lds_dwordx4 v[2:3], off
	s_add_i32 m0, s43, 0x400
	s_ashr_i32 s68, s67, 31
	s_add_u32 s69, s49, 0x800
	s_addc_u32 s64, s64, 0
	s_add_i32 s49, s46, 0xffffc800
	s_add_u32 s70, s62, s49
	s_addc_u32 s71, s63, 0
	v_lshl_add_u64 v[2:3], s[6:7], 0, v[164:165]
	s_and_b64 s[6:7], s[26:27], exec
	global_load_lds_dwordx4 v[2:3], off
	s_cselect_b32 s7, s64, s71
	s_cselect_b32 s6, s69, s70
	s_add_i32 m0, s43, 0x800
	s_add_u32 s62, s62, 0x2000
	s_addc_u32 s63, s63, 0
	s_add_u32 s53, s53, 0x4000
	s_addc_u32 s55, s55, 0
	s_add_u32 s64, s53, s46
	s_addc_u32 s69, s55, s47
	s_add_u32 s70, s62, s52
	s_addc_u32 s71, s63, 0
	v_lshl_add_u64 v[2:3], s[6:7], 0, v[164:165]
	s_and_b64 s[6:7], s[8:9], exec
	global_load_lds_dwordx4 v[2:3], off
	s_cselect_b32 s7, s69, s71
	s_cselect_b32 s6, s64, s70
	s_add_i32 m0, s43, 0x6000
	s_add_u32 s64, s53, s65
	s_addc_u32 s65, s55, s66
	s_add_u32 s66, s62, s48
	s_addc_u32 s69, s63, 0
	v_lshl_add_u64 v[2:3], s[6:7], 0, v[164:165]
	s_and_b64 s[6:7], s[26:27], exec
	global_load_lds_dwordx4 v[2:3], off
	s_cselect_b32 s7, s65, s69
	s_cselect_b32 s6, s64, s66
	s_add_i32 m0, s43, 0x6400
	s_add_u32 s53, s53, s67
	s_addc_u32 s55, s55, s68
	s_add_u32 s62, s62, s49
	s_addc_u32 s63, s63, 0
	v_lshl_add_u64 v[2:3], s[6:7], 0, v[164:165]
	s_and_b64 s[6:7], s[26:27], exec
	s_cselect_b32 s7, s55, s63
	s_cselect_b32 s6, s53, s62
	global_load_lds_dwordx4 v[2:3], off
	v_lshl_add_u64 v[2:3], s[6:7], 0, v[164:165]
	s_add_i32 m0, s43, 0x6800
	s_waitcnt vmcnt(0)
	v_mul_f32_e32 v51, 0x4f800000, v50
	global_load_lds_dwordx4 v[2:3], off
	s_waitcnt vmcnt(3)
	s_barrier
	ds_read_b128 v[2:5], v171
	ds_read_b128 v[6:9], v171 offset:1024
	s_waitcnt lgkmcnt(0)
	v_mfma_f32_32x32x64_f8f6f4 v[2:17], v[2:9], v[138:145], 0
	ds_read_b128 v[18:21], v171 offset:2048
	ds_read_b128 v[22:25], v171 offset:3072
	v_cmp_gt_f32_e32 vcc, s37, v50
	s_add_u32 s44, s44, s46
	s_addc_u32 s45, s45, s47
	v_cndmask_b32_e32 v59, v50, v51, vcc
	v_sqrt_f32_e32 v60, v59
	s_add_u32 s46, s50, s49
	s_addc_u32 s47, s51, 0
	s_add_u32 s48, s50, s48
	v_add_u32_e32 v61, -1, v60
	v_fma_f32 v62, -v61, v60, v59
	v_cmp_ge_f32_e64 s[6:7], 0, v62
	v_add_u32_e32 v62, 1, v60
	s_addc_u32 s49, s51, 0
	v_cndmask_b32_e64 v61, v60, v61, s[6:7]
	s_waitcnt lgkmcnt(0)
	v_mfma_f32_32x32x64_f8f6f4 v[2:17], v[18:25], v[146:153], v[2:17]
	ds_read_b128 v[18:21], v171 offset:4096
	ds_read_b128 v[22:25], v171 offset:5120
	ds_read_b128 v[34:37], v171 offset:6144
	ds_read_b128 v[38:41], v171 offset:7168
	v_fma_f32 v60, -v62, v60, v59
	v_cmp_lt_f32_e64 s[6:7], 0, v60
	s_add_u32 s50, s50, s52
	s_addc_u32 s51, s51, 0
	v_cndmask_b32_e64 v60, v61, v62, s[6:7]
	s_mov_b32 s55, 0
	s_mov_b32 s52, 0
	v_mov_b32_e32 v61, v163
	v_mov_b32_e32 v62, v163
	v_mov_b32_e32 v63, v163
	v_mov_b32_e32 v64, v163
	v_mov_b32_e32 v65, v163
	s_nop 3
	v_max3_f32 v2, v2, s39, v3
	s_waitcnt lgkmcnt(0)
	v_mfma_f32_32x32x64_f8f6f4 v[18:33], v[18:25], v[138:145], 0
	v_max3_f32 v2, v2, v4, v5
	v_max3_f32 v2, v2, v6, v7
	v_max3_f32 v2, v2, v8, v9
	v_max3_f32 v2, v2, v10, v11
	v_max3_f32 v2, v2, v12, v13
	v_max3_f32 v2, v2, v14, v15
	v_max3_f32 v2, v2, v16, v17
	v_mfma_f32_32x32x64_f8f6f4 v[18:33], v[34:41], v[146:153], v[18:33]
	ds_read_b128 v[34:37], v171 offset:8192
	ds_read_b128 v[38:41], v171 offset:9216
	ds_read_b128 v[50:53], v171 offset:10240
	ds_read_b128 v[54:57], v171 offset:11264
	s_waitcnt lgkmcnt(0)
	v_mfma_f32_32x32x64_f8f6f4 v[34:49], v[34:41], v[138:145], 0
	s_nop 13
	v_max3_f32 v2, v2, v18, v19
	v_max3_f32 v2, v2, v20, v21
	v_max3_f32 v18, v2, v22, v23
	v_max3_f32 v18, v18, v24, v25
	v_max3_f32 v18, v18, v26, v27
	v_max3_f32 v18, v18, v28, v29
	v_max3_f32 v18, v18, v30, v31
	v_max3_f32 v26, v18, v32, v33
	v_mov_b32_e32 v27, v163
	v_mov_b32_e32 v28, v163
	v_mov_b32_e32 v29, v163
	v_mov_b32_e32 v30, v163
	v_mov_b32_e32 v31, v163
	v_mov_b32_e32 v32, v163
	v_mov_b32_e32 v33, v163
	v_mfma_f32_32x32x64_f8f6f4 v[34:49], v[50:57], v[146:153], v[34:49]
	v_mul_f32_e32 v50, 0x37800000, v60
	v_cndmask_b32_e32 v60, v60, v50, vcc
	ds_read_b128 v[50:53], v171 offset:12288
	ds_read_b128 v[54:57], v171 offset:13312
	ds_read_b128 v[18:21], v171 offset:14336
	ds_read_b128 v[22:25], v171 offset:15360
	v_cmp_lt_i32_e32 vcc, v176, v177
	s_nop 12
	v_max3_f32 v26, v26, v34, v35
	s_waitcnt lgkmcnt(0)
	v_mfma_f32_32x32x64_f8f6f4 v[2:17], v[50:57], v[138:145], 0
	v_max3_f32 v26, v26, v36, v37
	v_max3_f32 v26, v26, v38, v39
	v_max3_f32 v26, v26, v40, v41
	v_max3_f32 v26, v26, v42, v43
	v_max3_f32 v26, v26, v44, v45
	v_max3_f32 v26, v26, v46, v47
	v_max3_f32 v26, v26, v48, v49
	v_mov_b32_e32 v50, 0
	v_mov_b32_e32 v51, v163
	v_mov_b32_e32 v52, v163
	v_mov_b32_e32 v53, v163
	v_mov_b32_e32 v54, v163
	v_mov_b32_e32 v55, v163
	v_mov_b32_e32 v56, v163
	v_mov_b32_e32 v57, v163
	v_mfma_f32_32x32x64_f8f6f4 v[2:17], v[18:25], v[146:153], v[2:17]
	v_mov_b32_e32 v18, 0
	v_mov_b32_e32 v19, v163
	v_mov_b32_e32 v20, v163
	v_mov_b32_e32 v21, v163
	v_mov_b32_e32 v22, v163
	v_mov_b32_e32 v23, v163
	v_mov_b32_e32 v24, v163
	v_mov_b32_e32 v25, v163
	s_nop 11
	v_max3_f32 v2, v26, v2, v3
	v_max3_f32 v2, v2, v4, v5
	v_max3_f32 v2, v2, v6, v7
	v_max3_f32 v2, v2, v8, v9
	v_max3_f32 v2, v2, v10, v11
	v_max3_f32 v2, v2, v12, v13
	v_max3_f32 v2, v2, v14, v15
	v_cndmask_b32_e32 v3, v175, v176, vcc
	v_max3_f32 v2, v2, v16, v17
	v_lshlrev_b32_e32 v3, 2, v3
	ds_bpermute_b32 v3, v3, v2
	v_cmp_class_f32_e32 vcc, v59, v172
	v_mov_b32_e32 v26, v163
	v_mov_b32_e32 v5, v163
	v_cndmask_b32_e32 v4, v60, v59, vcc
	s_waitcnt lgkmcnt(0)
	v_max_f32_e32 v3, v3, v3
	v_mul_f32_e32 v4, v58, v4
	v_max_f32_e32 v2, v2, v3
	v_fmamk_f32 v4, v4, 0x3f90a3d7, v173
	v_add_f32_e32 v2, 0x42800000, v2
	v_min_f32_e32 v2, v4, v2
	v_add_f32_e32 v2, 0xc2ec0000, v2
	v_xor_b32_e32 v34, 0x80000000, v2
	v_mov_b32_e32 v35, v34
	v_mov_b32_e32 v36, v34
	v_mov_b32_e32 v37, v34
	v_mov_b32_e32 v38, v34
	v_mov_b32_e32 v39, v34
	v_mov_b32_e32 v40, v34
	v_mov_b32_e32 v41, v34
	v_mov_b32_e32 v42, v34
	v_mov_b32_e32 v43, v34
	v_mov_b32_e32 v44, v34
	v_mov_b32_e32 v45, v34
	v_mov_b32_e32 v46, v34
	v_mov_b32_e32 v47, v34
	v_mov_b32_e32 v48, v34
	v_mov_b32_e32 v49, v34
	v_mov_b32_e32 v58, v163
	v_mov_b32_e32 v59, v163
	v_mov_b32_e32 v60, v163
	v_mov_b32_e32 v2, 0
	v_mov_b32_e32 v3, v163
	v_mov_b32_e32 v4, v163
	v_mov_b32_e32 v6, v163
	v_mov_b32_e32 v7, v163
	v_mov_b32_e32 v8, v163
	v_mov_b32_e32 v9, v163
	v_mov_b32_e32 v10, v163
	v_mov_b32_e32 v11, v163
	v_mov_b32_e32 v12, v163
	v_mov_b32_e32 v13, v163
	v_mov_b32_e32 v14, v163
	v_mov_b32_e32 v15, v163
	v_mov_b32_e32 v16, v163
	v_mov_b32_e32 v17, v163
	v_mov_b32_e32 v86, v163
	v_mov_b32_e32 v87, v163
	v_mov_b32_e32 v88, v163
	v_mov_b32_e32 v89, v163
	v_mov_b32_e32 v90, v163
	v_mov_b32_e32 v91, v163
	v_mov_b32_e32 v92, v163
	v_mov_b32_e32 v93, v163
	v_mov_b32_e32 v94, v163
	v_mov_b32_e32 v95, v163
	v_mov_b32_e32 v96, v163
	v_mov_b32_e32 v97, v163
	v_mov_b32_e32 v98, v163
	v_mov_b32_e32 v99, v163
	v_mov_b32_e32 v100, v163
	v_mov_b32_e32 v101, v163
	v_mov_b32_e32 v102, v163
	v_mov_b32_e32 v103, v163
	v_mov_b32_e32 v104, v163
	v_mov_b32_e32 v105, v163
	v_mov_b32_e32 v106, v163
	v_mov_b32_e32 v107, v163
	v_mov_b32_e32 v108, v163
	v_mov_b32_e32 v109, v163
	v_mov_b32_e32 v110, v163
	v_mov_b32_e32 v111, v163
	v_mov_b32_e32 v112, v163
	v_mov_b32_e32 v113, v163
	v_mov_b32_e32 v114, v163
	v_mov_b32_e32 v115, v163
	v_mov_b32_e32 v116, v163
	v_mov_b32_e32 v117, v163
	v_mov_b32_e32 v228, v163
	v_mov_b32_e32 v229, v163
	v_mov_b32_e32 v230, v163
	v_mov_b32_e32 v231, v163
	v_mov_b32_e32 v232, v163
	v_mov_b32_e32 v233, v163
	v_mov_b32_e32 v234, v163
	v_mov_b32_e32 v235, v163
	v_mov_b32_e32 v236, v163
	v_mov_b32_e32 v237, v163
	v_mov_b32_e32 v238, v163
	v_mov_b32_e32 v239, v163
	v_mov_b32_e32 v240, v163
	v_mov_b32_e32 v241, v163
	v_mov_b32_e32 v242, v163
	v_mov_b32_e32 v243, v163
	s_add_u32 s98, s18, s44
	s_addc_u32 s99, s19, s45
	s_add_u32 s98, s98, 0x23076100
	s_addc_u32 s99, s99, 0
	s_add_u32 s100, s18, s50
	s_addc_u32 s101, s19, s51
	s_add_u32 s100, s100, 0x26132100
	s_addc_u32 s101, s101, 0
	s_movk_i32 s74, 0x2000
	s_and_b64 s[62:63], s[8:9], exec
	s_cselect_b32 s63, s99, s101
	s_cselect_b32 s62, s98, s100
	s_cselect_b32 s74, 0x4000, s74
	s_add_u32 s68, s62, s74
	s_addc_u32 s69, s63, 0
	s_lshl_b32 s74, s74, 1
	s_add_u32 s98, s18, s44
	s_addc_u32 s99, s19, s45
	s_add_u32 s98, s98, 0x23076500
	s_addc_u32 s99, s99, 0
	s_add_u32 s100, s18, s48
	s_addc_u32 s101, s19, s49
	s_add_u32 s100, s100, 0x26132100
	s_addc_u32 s101, s101, 0
	s_movk_i32 s75, 0x2000
	s_and_b64 s[64:65], s[26:27], exec
	s_cselect_b32 s65, s99, s101
	s_cselect_b32 s64, s98, s100
	s_cselect_b32 s75, 0x4000, s75
	s_add_u32 s70, s64, s75
	s_addc_u32 s71, s65, 0
	s_lshl_b32 s75, s75, 1
	s_add_u32 s98, s18, s44
	s_addc_u32 s99, s19, s45
	s_add_u32 s98, s98, 0x23076900
	s_addc_u32 s99, s99, 0
	s_add_u32 s100, s18, s46
	s_addc_u32 s101, s19, s47
	s_add_u32 s100, s100, 0x26132100
	s_addc_u32 s101, s101, 0
	s_movk_i32 s76, 0x2000
	s_and_b64 s[66:67], s[26:27], exec
	s_cselect_b32 s67, s99, s101
	s_cselect_b32 s66, s98, s100
	s_cselect_b32 s76, 0x4000, s76
	s_add_u32 s72, s66, s76
	s_addc_u32 s73, s67, 0
	s_lshl_b32 s76, s76, 1
	s_mov_b64 s[98:99], 0
	v_mov_b32_e32 v167, v171
	v_add_u32_e32 v127, 0xc000, v171
	s_waitcnt vmcnt(0) lgkmcnt(0)
	s_barrier
	ds_read_b128 v[190:193], v167
	ds_read_b128 v[194:197], v167 offset:1024
	ds_read_b128 v[198:201], v167 offset:2048
	ds_read_b128 v[202:205], v167 offset:3072
	ds_read_b128 v[206:209], v167 offset:4096
	ds_read_b128 v[210:213], v167 offset:5120
	ds_read_b128 v[220:223], v167 offset:6144
	ds_read_b128 v[224:227], v167 offset:7168
	s_waitcnt lgkmcnt(0)
	s_branch .LBB0_1289
.LBB0_1290:
	v_swap_b32 v167, v127
.LBB0_1289:
	s_cmpk_gt_u32 s52, 0x7f
	s_cselect_b64 vcc, 0, exec
	s_add_i32 s52, s52, 2
	s_xor_b32 s55, s55, 2
	s_cmp_lg_u64 s[98:99], 0
	s_cbranch_scc1 .Lslow_mla0_0
.Lback_mla0_0:
	v_cvt_pk_u8_f32 v118, v86, 0, 0
	v_cvt_pk_u8_f32 v119, v90, 0, 0
	v_cvt_pk_u8_f32 v120, v94, 0, 0
	v_cvt_pk_u8_f32 v121, v98, 0, 0
	v_cvt_pk_u8_f32 v118, v87, 1, v118
	v_cvt_pk_u8_f32 v119, v91, 1, v119
	v_cvt_pk_u8_f32 v120, v95, 1, v120
	v_cvt_pk_u8_f32 v121, v99, 1, v121
	s_waitcnt lgkmcnt(10)
	v_mfma_f32_32x32x64_f8f6f4 v[54:69], v[190:197], v[138:145], v[34:49]
	v_cvt_pk_u8_f32 v118, v88, 2, v118
	v_cvt_pk_u8_f32 v119, v92, 2, v119
	v_cvt_pk_u8_f32 v120, v96, 2, v120
	v_cvt_pk_u8_f32 v121, v100, 2, v121
	v_cvt_pk_u8_f32 v118, v89, 3, v118
	v_cvt_pk_u8_f32 v119, v93, 3, v119
	v_cvt_pk_u8_f32 v120, v97, 3, v120
	v_cvt_pk_u8_f32 v121, v101, 3, v121
	s_waitcnt lgkmcnt(8)
	v_mfma_f32_32x32x64_f8f6f4 v[54:69], v[198:205], v[146:153], v[54:69]
	v_cvt_pk_u8_f32 v122, v102, 0, 0
	v_cvt_pk_u8_f32 v123, v106, 0, 0
	v_cvt_pk_u8_f32 v124, v110, 0, 0
	v_cvt_pk_u8_f32 v125, v114, 0, 0
	v_cvt_pk_u8_f32 v122, v103, 1, v122
	v_cvt_pk_u8_f32 v123, v107, 1, v123
	v_cvt_pk_u8_f32 v124, v111, 1, v124
	v_cvt_pk_u8_f32 v125, v115, 1, v125
	s_waitcnt lgkmcnt(6)
	v_mfma_f32_32x32x64_f8f6f4 v[70:85], v[206:213], v[138:145], v[34:49]
	v_cvt_pk_u8_f32 v122, v104, 2, v122
	v_cvt_pk_u8_f32 v123, v108, 2, v123
	v_cvt_pk_u8_f32 v124, v112, 2, v124
	v_cvt_pk_u8_f32 v125, v116, 2, v125
	v_cvt_pk_u8_f32 v122, v105, 3, v122
	v_cvt_pk_u8_f32 v123, v109, 3, v123
	v_cvt_pk_u8_f32 v124, v113, 3, v124
	v_cvt_pk_u8_f32 v125, v117, 3, v125
	s_waitcnt lgkmcnt(4)
	v_mfma_f32_32x32x64_f8f6f4 v[70:85], v[220:227], v[146:153], v[70:85]
	s_nop 0
	s_waitcnt lgkmcnt(0)
	s_barrier
	v_mfma_f32_32x32x64_f8f6f4 v[18:33], v[228:235], v[118:125], v[18:33] blgp:1
	ds_read_b128 v[190:193], v167 offset:8192
	ds_read_b128 v[194:197], v167 offset:9216
	ds_read_b128 v[198:201], v167 offset:10240
	ds_read_b128 v[202:205], v167 offset:11264
	s_cbranch_vccz .Ldma_mla0_skip0
	s_mul_i32 s101, s55, 0x6000
	s_add_i32 s101, s101, s43
	s_mov_b32 m0, s101
	s_nop 0
	global_load_lds_dwordx4 v164, s[62:63]

.Lback_mla0_3:
	v_cvt_pk_u8_f32 v118, v54, 0, 0
	v_cvt_pk_u8_f32 v119, v58, 0, 0
	v_cvt_pk_u8_f32 v120, v62, 0, 0
	v_cvt_pk_u8_f32 v121, v66, 0, 0
	v_cvt_pk_u8_f32 v118, v55, 1, v118
	v_cvt_pk_u8_f32 v119, v59, 1, v119
	v_cvt_pk_u8_f32 v120, v63, 1, v120
	v_cvt_pk_u8_f32 v121, v67, 1, v121
	s_waitcnt lgkmcnt(4)
	v_mfma_f32_32x32x64_f8f6f4 v[86:101], v[190:197], v[138:145], v[34:49]
	v_cvt_pk_u8_f32 v118, v56, 2, v118
	v_cvt_pk_u8_f32 v119, v60, 2, v119
	v_cvt_pk_u8_f32 v120, v64, 2, v120
	v_cvt_pk_u8_f32 v121, v68, 2, v121
	v_cvt_pk_u8_f32 v118, v57, 3, v118
	v_cvt_pk_u8_f32 v119, v61, 3, v119
	v_cvt_pk_u8_f32 v120, v65, 3, v120
	v_cvt_pk_u8_f32 v121, v69, 3, v121
	v_mfma_f32_32x32x64_f8f6f4 v[86:101], v[198:205], v[146:153], v[86:101]
	v_cvt_pk_u8_f32 v122, v70, 0, 0
	v_cvt_pk_u8_f32 v123, v74, 0, 0
	v_cvt_pk_u8_f32 v124, v78, 0, 0
	v_cvt_pk_u8_f32 v125, v82, 0, 0
	v_cvt_pk_u8_f32 v122, v71, 1, v122
	v_cvt_pk_u8_f32 v123, v75, 1, v123
	v_cvt_pk_u8_f32 v124, v79, 1, v124
	v_cvt_pk_u8_f32 v125, v83, 1, v125
	v_mfma_f32_32x32x64_f8f6f4 v[102:117], v[206:213], v[138:145], v[34:49]
	v_cvt_pk_u8_f32 v122, v72, 2, v122
	v_cvt_pk_u8_f32 v123, v76, 2, v123
	v_cvt_pk_u8_f32 v124, v80, 2, v124
	v_cvt_pk_u8_f32 v125, v84, 2, v125
	v_cvt_pk_u8_f32 v122, v73, 3, v122
	v_cvt_pk_u8_f32 v123, v77, 3, v123
	v_cvt_pk_u8_f32 v124, v81, 3, v124
	v_cvt_pk_u8_f32 v125, v85, 3, v125
	v_mfma_f32_32x32x64_f8f6f4 v[102:117], v[220:227], v[146:153], v[102:117]
	s_nop 0
	s_waitcnt lgkmcnt(0)
	v_mfma_f32_32x32x64_f8f6f4 v[18:33], v[228:235], v[118:125], v[18:33] blgp:1
	v_mfma_f32_32x32x64_f8f6f4 v[2:17], v[236:243], v[118:125], v[2:17] blgp:1
	v_max3_f32 v126, v86, v87, v88
	v_max3_f32 v126, v126, v89, v90
	v_max3_f32 v126, v126, v91, v92
	v_max3_f32 v126, v126, v93, v94
	v_max3_f32 v126, v126, v95, v96
	v_max3_f32 v126, v126, v97, v98
	v_max3_f32 v126, v126, v99, v100
	v_max3_f32 v126, v126, v101, v101
	v_mfma_f32_16x16x128_f8f6f4 v[50:53], v[154:161], v[118:125], v[50:53] blgp:1
	s_nop 6
	v_max3_f32 v126, v126, v102, v103
	v_max3_f32 v126, v126, v104, v105
	v_max3_f32 v126, v126, v106, v107
	v_max3_f32 v126, v126, v108, v109
	v_max3_f32 v126, v126, v110, v111
	v_max3_f32 v126, v126, v112, v113
	v_max3_f32 v126, v126, v114, v115
	v_max3_f32 v126, v126, v116, v117
	v_cmp_gt_f32_e64 s[98:99], v126, v180
	s_waitcnt vmcnt(0)
	s_barrier
	ds_read_b128 v[190:193], v127
	ds_read_b128 v[194:197], v127 offset:1024
	ds_read_b128 v[198:201], v127 offset:2048
	ds_read_b128 v[202:205], v127 offset:3072
	ds_read_b128 v[206:209], v127 offset:4096
	ds_read_b128 v[210:213], v127 offset:5120
	ds_read_b128 v[220:223], v127 offset:6144
	ds_read_b128 v[224:227], v127 offset:7168
	ds_read_b128 v[228:231], v167 offset:45056
	ds_read_b128 v[232:235], v167 offset:46080
	ds_read_b128 v[236:239], v167 offset:47104
	ds_read_b128 v[240:243], v167 offset:48128
	s_cbranch_vccnz .LBB0_1290
	s_waitcnt lgkmcnt(0)
	s_cmp_lg_u64 s[98:99], 0
	s_cbranch_scc1 .Lslow_mla0_4

.LBB0_1298:
	s_ashr_i32 s10, s8, 6
	s_and_b32 s11, s8, 63
	s_lshr_b32 s8, s42, 1
	s_add_i32 s22, s8, s34
	s_lshl_b32 s8, s42, 5
	s_and_b32 s8, s8, 32
	s_add_i32 s26, s8, s31
	s_and_b64 s[8:9], s[16:17], exec
	s_cselect_b32 s9, s22, s10
	s_cselect_b32 s8, s26, s11
	s_ashr_i32 s10, s9, 3
	s_mul_i32 s11, s10, 0x4100
	s_lshl_b32 s8, s8, 8
	s_add_i32 s11, s11, s8
	v_add_u32_e32 v166, s11, v170
	v_ashrrev_i32_e32 v167, 31, v166
	s_and_b32 s43, s9, 7
	v_lshlrev_b64 v[2:3], 9, v[166:167]
	v_lshl_add_u64 v[2:3], s[18:19], 0, v[2:3]
	s_lshl_b32 s22, s43, 6
	v_lshl_add_u64 v[2:3], v[2:3], 0, s[22:23]
	s_lshl_b32 s22, s43, 2
	s_mul_i32 s44, s9, 0x104000
	s_mul_hi_i32 s45, s9, 0x104000
	s_add_u32 s53, s35, s44
	s_addc_u32 s55, s36, s45
	s_lshl_b32 s8, s10, 2
	s_bfe_u32 s10, s9, 0x20001
	s_or_b32 s50, s8, s10
	s_mul_hi_i32 s51, s50, 0x208000
	s_mul_i32 s50, s50, 0x208000
	s_add_u32 s62, s37, s50
	s_addc_u32 s63, s38, s51
	s_add_i32 s8, s9, 16
	s_ashr_i32 s9, s8, 31
	v_lshlrev_b64 v[4:5], 5, v[166:167]
	s_lshl_b64 s[8:9], s[8:9], 2
	v_lshl_add_u64 v[4:5], s[12:13], 0, v[4:5]
	s_add_u32 s8, s3, s8
	v_lshl_add_u64 v[4:5], v[4:5], 0, s[22:23]
	s_addc_u32 s9, s28, s9
	global_load_dword v42, v[4:5], off
	global_load_dword v18, v163, s[8:9]
	v_lshl_add_u64 v[2:3], v[2:3], 0, v[210:211]
	global_load_dwordx4 v[150:153], v[2:3], off offset:16
	global_load_dwordx4 v[146:149], v[2:3], off
	v_readfirstlane_b32 s8, v1
	s_ashr_i32 s26, s8, 6
	s_cmp_lt_i32 s26, 3
	s_mul_i32 s46, s26, 0xc00
	s_cselect_b64 s[10:11], -1, 0
	s_add_i32 s52, s46, 0xffffe000
	s_add_u32 s22, s62, s52
	s_addc_u32 s27, s63, 0
	s_ashr_i32 s47, s46, 31
	s_add_u32 s49, s53, s46
	s_addc_u32 s64, s55, s47
	s_and_b64 s[8:9], s[10:11], exec
	s_cselect_b32 s9, s64, s27
	s_cselect_b32 s8, s49, s22
	s_add_i32 s65, s46, 0x400
	s_add_i32 s22, s46, 0
	s_ashr_i32 s66, s65, 31
	s_add_u32 s27, s49, 0x400
	s_addc_u32 s67, s64, 0
	s_add_i32 s48, s46, 0xffffe400
	s_add_u32 s68, s62, s48
	s_addc_u32 s69, s63, 0
	v_lshl_add_u64 v[2:3], s[8:9], 0, v[164:165]
	s_mov_b32 m0, s22
	s_and_b64 s[8:9], s[10:11], exec
	v_lshrrev_b32 v154, 2, v0
	v_xor_b32 v154, v154, v0
	v_bfe_u32 v154, v154, 2, 1
	v_add_u32 v154, -1, v154
	v_and_b32 v154, 0x38383838, v154
	v_mov_b32 v155, v154
	v_mov_b32 v156, v154
	v_mov_b32 v157, v154
	v_mov_b32 v158, v154
	v_mov_b32 v159, v154
	v_mov_b32 v160, v154
	v_mov_b32 v161, v154
	global_load_lds_dwordx4 v[2:3], off
	s_cselect_b32 s9, s67, s69
	s_cselect_b32 s8, s27, s68
	s_add_i32 m0, s22, 0x400
	s_cmp_lt_i32 s26, 2
	s_cselect_b64 s[26:27], -1, 0
	s_add_i32 s67, s46, 0x800
	s_ashr_i32 s68, s67, 31
	s_add_u32 s69, s49, 0x800
	s_addc_u32 s64, s64, 0
	s_add_i32 s49, s46, 0xffffe800
	s_add_u32 s70, s62, s49
	s_addc_u32 s71, s63, 0
	v_lshl_add_u64 v[2:3], s[8:9], 0, v[164:165]
	s_and_b64 s[8:9], s[26:27], exec
	global_load_lds_dwordx4 v[2:3], off
	s_cselect_b32 s9, s64, s71
	s_cselect_b32 s8, s69, s70
	s_add_i32 m0, s22, 0x800
	s_add_u32 s62, s62, 0x4000
	s_addc_u32 s63, s63, 0
	s_add_u32 s53, s53, 0x2000
	s_addc_u32 s55, s55, 0
	s_add_u32 s64, s53, s46
	s_addc_u32 s69, s55, s47
	s_add_u32 s70, s62, s52
	s_addc_u32 s71, s63, 0
	v_lshl_add_u64 v[2:3], s[8:9], 0, v[164:165]
	s_and_b64 s[8:9], s[10:11], exec
	global_load_lds_dwordx4 v[2:3], off
	s_cselect_b32 s9, s69, s71
	s_cselect_b32 s8, s64, s70
	s_add_i32 m0, s22, 0x6000
	s_add_u32 s64, s53, s65
	s_addc_u32 s65, s55, s66
	s_add_u32 s66, s62, s48
	s_addc_u32 s69, s63, 0
	v_lshl_add_u64 v[2:3], s[8:9], 0, v[164:165]
	s_and_b64 s[8:9], s[10:11], exec
	global_load_lds_dwordx4 v[2:3], off
	s_cselect_b32 s9, s65, s69
	s_cselect_b32 s8, s64, s66
	s_add_i32 m0, s22, 0x6400
	s_add_u32 s53, s53, s67
	s_addc_u32 s55, s55, s68
	s_add_u32 s62, s62, s49
	s_addc_u32 s63, s63, 0
	v_lshl_add_u64 v[2:3], s[8:9], 0, v[164:165]
	s_and_b64 s[8:9], s[26:27], exec
	s_cselect_b32 s9, s55, s63
	s_cselect_b32 s8, s53, s62
	global_load_lds_dwordx4 v[2:3], off
	v_lshl_add_u64 v[2:3], s[8:9], 0, v[164:165]
	s_add_i32 m0, s22, 0x6800
	s_waitcnt vmcnt(0)
	v_mul_f32_e32 v19, 0x4f800000, v18
	global_load_lds_dwordx4 v[2:3], off
	s_waitcnt vmcnt(3)
	s_barrier
	ds_read_b128 v[2:5], v171
	ds_read_b128 v[6:9], v171 offset:1024
	v_cmp_gt_f32_e32 vcc, s39, v18
	s_waitcnt lgkmcnt(0)
	v_mfma_f32_32x32x64_f8f6f4 v[2:17], v[2:9], v[146:153], 0
	v_cndmask_b32_e32 v43, v18, v19, vcc
	v_sqrt_f32_e32 v26, v43
	ds_read_b128 v[18:21], v171 offset:2048
	ds_read_b128 v[22:25], v171 offset:3072
	s_add_u32 s44, s44, s46
	s_addc_u32 s45, s45, s47
	v_add_u32_e32 v27, -1, v26
	v_fma_f32 v28, -v27, v26, v43
	v_cmp_ge_f32_e64 s[8:9], 0, v28
	v_add_u32_e32 v28, 1, v26
	s_add_u32 s46, s50, s49
	v_cndmask_b32_e64 v27, v26, v27, s[8:9]
	v_fma_f32 v26, -v28, v26, v43
	v_cmp_lt_f32_e64 s[8:9], 0, v26
	s_addc_u32 s47, s51, 0
	s_add_u32 s48, s50, s48
	v_cndmask_b32_e64 v34, v27, v28, s[8:9]
	s_waitcnt lgkmcnt(0)
	v_mfma_f32_32x32x64_f8f6f4 v[18:33], v[18:25], v[146:153], 0
	v_max3_f32 v2, v2, s40, v3
	v_max3_f32 v2, v2, v4, v5
	v_max3_f32 v2, v2, v6, v7
	v_max3_f32 v2, v2, v8, v9
	v_mul_f32_e32 v35, 0x37800000, v34
	v_max3_f32 v2, v2, v10, v11
	v_cndmask_b32_e32 v44, v34, v35, vcc
	ds_read_b128 v[34:37], v171 offset:4096
	ds_read_b128 v[38:41], v171 offset:5120
	v_max3_f32 v2, v2, v12, v13
	v_max3_f32 v2, v2, v14, v15
	v_max3_f32 v2, v2, v16, v17
	v_cmp_lt_i32_e32 vcc, v176, v177
	s_addc_u32 s49, s51, 0
	s_add_u32 s50, s50, s52
	s_addc_u32 s51, s51, 0
	s_nop 3
	v_max3_f32 v2, v2, v18, v19
	v_max3_f32 v2, v2, v20, v21
	v_max3_f32 v18, v2, v22, v23
	s_waitcnt lgkmcnt(0)
	v_mfma_f32_32x32x64_f8f6f4 v[2:17], v[34:41], v[146:153], 0
	v_max3_f32 v18, v18, v24, v25
	v_max3_f32 v18, v18, v26, v27
	v_max3_f32 v18, v18, v28, v29
	v_max3_f32 v18, v18, v30, v31
	v_max3_f32 v26, v18, v32, v33
	ds_read_b128 v[18:21], v171 offset:6144
	ds_read_b128 v[22:25], v171 offset:7168
	s_mov_b32 s55, 0
	s_mov_b32 s52, 0
	v_mov_b32_e32 v27, v163
	v_mov_b32_e32 v28, v163
	v_mov_b32_e32 v29, v163
	v_mov_b32_e32 v30, v163
	v_mov_b32_e32 v31, v163
	v_mov_b32_e32 v32, v163
	v_mov_b32_e32 v33, v163
	s_nop 3
	v_max3_f32 v2, v26, v2, v3
	v_max3_f32 v2, v2, v4, v5
	v_max3_f32 v2, v2, v6, v7
	v_max3_f32 v2, v2, v8, v9
	v_max3_f32 v2, v2, v10, v11
	v_max3_f32 v2, v2, v12, v13
	v_max3_f32 v2, v2, v14, v15
	v_max3_f32 v26, v2, v16, v17
	s_waitcnt lgkmcnt(0)
	v_mfma_f32_32x32x64_f8f6f4 v[2:17], v[18:25], v[146:153], 0
	v_mov_b32_e32 v18, 0
	v_mov_b32_e32 v19, v163
	v_mov_b32_e32 v20, v163
	v_mov_b32_e32 v21, v163
	v_mov_b32_e32 v22, v163
	v_mov_b32_e32 v23, v163
	v_mov_b32_e32 v24, v163
	v_mov_b32_e32 v25, v163
	v_mov_b32_e32 v34, 0
	v_mov_b32_e32 v35, v163
	v_mov_b32_e32 v36, v163
	v_mov_b32_e32 v37, v163
	v_mov_b32_e32 v38, v163
	v_mov_b32_e32 v39, v163
	v_mov_b32_e32 v40, v163
	s_nop 4
	v_max3_f32 v2, v26, v2, v3
	v_max3_f32 v2, v2, v4, v5
	v_max3_f32 v2, v2, v6, v7
	v_max3_f32 v2, v2, v8, v9
	v_max3_f32 v2, v2, v10, v11
	v_max3_f32 v2, v2, v12, v13
	v_max3_f32 v2, v2, v14, v15
	v_cndmask_b32_e32 v3, v175, v176, vcc
	v_max3_f32 v2, v2, v16, v17
	v_lshlrev_b32_e32 v3, 2, v3
	ds_bpermute_b32 v3, v3, v2
	v_cmp_class_f32_e32 vcc, v43, v172
	v_mov_b32_e32 v5, v163
	v_mov_b32_e32 v6, v163
	v_cndmask_b32_e32 v4, v44, v43, vcc
	s_waitcnt lgkmcnt(0)
	v_max_f32_e32 v3, v3, v3
	v_mul_f32_e32 v4, v42, v4
	v_max_f32_e32 v2, v2, v3
	v_fmamk_f32 v4, v4, 0x3f90a3d7, v173
	v_add_f32_e32 v2, 0x42800000, v2
	v_min_f32_e32 v2, v4, v2
	v_add_f32_e32 v2, 0xc2ec0000, v2
	v_xor_b32_e32 v50, 0x80000000, v2
	v_mov_b32_e32 v51, v50
	v_mov_b32_e32 v52, v50
	v_mov_b32_e32 v53, v50
	v_mov_b32_e32 v54, v50
	v_mov_b32_e32 v55, v50
	v_mov_b32_e32 v56, v50
	v_mov_b32_e32 v57, v50
	v_mov_b32_e32 v58, v50
	v_mov_b32_e32 v59, v50
	v_mov_b32_e32 v60, v50
	v_mov_b32_e32 v61, v50
	v_mov_b32_e32 v62, v50
	v_mov_b32_e32 v63, v50
	v_mov_b32_e32 v64, v50
	v_mov_b32_e32 v65, v50
	v_mov_b32_e32 v2, 0
	v_mov_b32_e32 v3, v163
	v_mov_b32_e32 v4, v163
	v_mov_b32_e32 v7, v163
	v_mov_b32_e32 v8, v163
	v_mov_b32_e32 v9, v163
	v_mov_b32_e32 v10, v163
	v_mov_b32_e32 v11, v163
	v_mov_b32_e32 v12, v163
	v_mov_b32_e32 v13, v163
	v_mov_b32_e32 v14, v163
	v_mov_b32_e32 v15, v163
	v_mov_b32_e32 v16, v163
	v_mov_b32_e32 v17, v163
	v_mov_b32_e32 v26, v163
	v_mov_b32_e32 v41, v163
	v_mov_b32_e32 v42, v163
	v_mov_b32_e32 v43, v163
	v_mov_b32_e32 v44, v163
	v_mov_b32_e32 v45, v163
	v_mov_b32_e32 v46, v163
	v_mov_b32_e32 v47, v163
	v_mov_b32_e32 v48, v163
	v_mov_b32_e32 v49, v163
	v_mov_b32_e32 v66, 0
	v_mov_b32_e32 v67, v163
	v_mov_b32_e32 v68, v163
	v_mov_b32_e32 v69, v163
	v_mov_b32_e32 v70, v163
	v_mov_b32_e32 v71, v163
	v_mov_b32_e32 v72, v163
	v_mov_b32_e32 v73, v163
	v_mov_b32_e32 v74, v163
	v_mov_b32_e32 v75, v163
	v_mov_b32_e32 v76, v163
	v_mov_b32_e32 v77, v163
	v_mov_b32_e32 v78, v163
	v_mov_b32_e32 v79, v163
	v_mov_b32_e32 v80, v163
	v_mov_b32_e32 v81, v163
	v_mov_b32_e32 v82, 0
	v_mov_b32_e32 v83, v163
	v_mov_b32_e32 v84, v163
	v_mov_b32_e32 v85, v163
	v_mov_b32_e32 v86, v163
	v_mov_b32_e32 v87, v163
	v_mov_b32_e32 v88, v163
	v_mov_b32_e32 v89, v163
	v_mov_b32_e32 v90, v163
	v_mov_b32_e32 v91, v163
	v_mov_b32_e32 v92, v163
	v_mov_b32_e32 v93, v163
	v_mov_b32_e32 v94, v163
	v_mov_b32_e32 v95, v163
	v_mov_b32_e32 v96, v163
	v_mov_b32_e32 v97, v163
	v_mov_b32_e32 v142, v210
	v_mov_b32_e32 v143, v211
	v_mov_b32_e32 v144, v218
	v_mov_b32_e32 v145, v219
	v_mov_b32_e32 v118, v163
	v_mov_b32_e32 v119, v163
	v_mov_b32_e32 v120, v163
	v_mov_b32_e32 v121, v163
	v_mov_b32_e32 v122, v163
	v_mov_b32_e32 v123, v163
	v_mov_b32_e32 v124, v163
	v_mov_b32_e32 v125, v163
	v_mov_b32_e32 v126, v163
	v_mov_b32_e32 v127, v163
	v_mov_b32_e32 v128, v163
	v_mov_b32_e32 v129, v163
	v_mov_b32_e32 v130, v163
	v_mov_b32_e32 v131, v163
	v_mov_b32_e32 v132, v163
	v_mov_b32_e32 v133, v163
	v_mov_b32_e32 v180, v163
	v_mov_b32_e32 v181, v163
	v_mov_b32_e32 v182, v163
	v_mov_b32_e32 v183, v163
	v_mov_b32_e32 v184, v163
	v_mov_b32_e32 v185, v163
	v_mov_b32_e32 v186, v163
	v_mov_b32_e32 v187, v163
	v_mov_b32_e32 v188, v163
	v_mov_b32_e32 v189, v163
	v_mov_b32_e32 v190, v163
	v_mov_b32_e32 v191, v163
	v_mov_b32_e32 v192, v163
	v_mov_b32_e32 v193, v163
	v_mov_b32_e32 v194, v163
	v_mov_b32_e32 v195, v163
	v_mov_b32_e32 v220, v163
	v_mov_b32_e32 v221, v163
	v_mov_b32_e32 v222, v163
	v_mov_b32_e32 v223, v163
	v_mov_b32_e32 v224, v163
	v_mov_b32_e32 v225, v163
	v_mov_b32_e32 v226, v163
	v_mov_b32_e32 v227, v163
	v_mov_b32_e32 v228, v163
	v_mov_b32_e32 v229, v163
	v_mov_b32_e32 v230, v163
	v_mov_b32_e32 v231, v163
	v_mov_b32_e32 v232, v163
	v_mov_b32_e32 v233, v163
	v_mov_b32_e32 v234, v163
	v_mov_b32_e32 v235, v163
	v_mov_b32_e32 v236, v163
	v_mov_b32_e32 v237, v163
	v_mov_b32_e32 v238, v163
	v_mov_b32_e32 v239, v163
	v_mov_b32_e32 v240, v163
	v_mov_b32_e32 v241, v163
	v_mov_b32_e32 v242, v163
	v_mov_b32_e32 v243, v163
	v_mov_b32_e32 v244, v163
	v_mov_b32_e32 v245, v163
	v_mov_b32_e32 v246, v163
	v_mov_b32_e32 v247, v163
	v_mov_b32_e32 v248, v163
	v_mov_b32_e32 v249, v163
	v_mov_b32_e32 v250, v163
	v_mov_b32_e32 v251, v163
	s_add_u32 s98, s29, s44
	s_addc_u32 s99, s30, s45
	s_add_u32 s98, s98, 0x36532100
	s_addc_u32 s99, s99, 0
	s_add_u32 s100, s29, s50
	s_addc_u32 s101, s30, s51
	s_add_u32 s100, s100, 0x385b6100
	s_addc_u32 s101, s101, 0
	s_movk_i32 s74, 0x4000
	s_and_b64 s[62:63], s[10:11], exec
	s_cselect_b32 s63, s99, s101
	s_cselect_b32 s62, s98, s100
	s_cselect_b32 s74, 0x2000, s74
	s_add_u32 s68, s62, s74
	s_addc_u32 s69, s63, 0
	s_lshl_b32 s74, s74, 1
	s_add_u32 s98, s29, s44
	s_addc_u32 s99, s30, s45
	s_add_u32 s98, s98, 0x36532500
	s_addc_u32 s99, s99, 0
	s_add_u32 s100, s29, s48
	s_addc_u32 s101, s30, s49
	s_add_u32 s100, s100, 0x385b6100
	s_addc_u32 s101, s101, 0
	s_movk_i32 s75, 0x4000
	s_and_b64 s[64:65], s[10:11], exec
	s_cselect_b32 s65, s99, s101
	s_cselect_b32 s64, s98, s100
	s_cselect_b32 s75, 0x2000, s75
	s_add_u32 s70, s64, s75
	s_addc_u32 s71, s65, 0
	s_lshl_b32 s75, s75, 1
	s_add_u32 s98, s29, s44
	s_addc_u32 s99, s30, s45
	s_add_u32 s98, s98, 0x36532900
	s_addc_u32 s99, s99, 0
	s_add_u32 s100, s29, s46
	s_addc_u32 s101, s30, s47
	s_add_u32 s100, s100, 0x385b6100
	s_addc_u32 s101, s101, 0
	s_movk_i32 s76, 0x4000
	s_and_b64 s[66:67], s[26:27], exec
	s_cselect_b32 s67, s99, s101
	s_cselect_b32 s66, s98, s100
	s_cselect_b32 s76, 0x2000, s76
	s_add_u32 s72, s66, s76
	s_addc_u32 s73, s67, 0
	s_lshl_b32 s76, s76, 1
	s_mov_b64 s[98:99], 0
	v_mov_b32_e32 v179, v171
	v_add_u32_e32 v135, 0xc000, v171
	s_waitcnt vmcnt(0) lgkmcnt(0)
	s_barrier
	ds_read_b128 v[204:207], v179
	ds_read_b128 v[208:211], v179 offset:1024
	ds_read_b128 v[212:215], v179 offset:2048
	ds_read_b128 v[216:219], v179 offset:3072
	s_waitcnt lgkmcnt(0)
	s_branch .LBB0_1299
.LBB0_1300:
	v_swap_b32 v179, v135

.Lback_dif0_0:
	v_cvt_pk_u8_f32 v196, v118, 0, 0
	v_cvt_pk_u8_f32 v197, v122, 0, 0
	v_cvt_pk_u8_f32 v198, v126, 0, 0
	v_cvt_pk_u8_f32 v199, v130, 0, 0
	v_cvt_pk_u8_f32 v196, v119, 1, v196
	v_cvt_pk_u8_f32 v197, v123, 1, v197
	v_cvt_pk_u8_f32 v198, v127, 1, v198
	v_cvt_pk_u8_f32 v199, v131, 1, v199
	s_waitcnt lgkmcnt(10)
	v_mfma_f32_32x32x64_f8f6f4 v[86:101], v[204:211], v[146:153], v[50:65]
	v_cvt_pk_u8_f32 v196, v120, 2, v196
	v_cvt_pk_u8_f32 v197, v124, 2, v197
	v_cvt_pk_u8_f32 v198, v128, 2, v198
	v_cvt_pk_u8_f32 v199, v132, 2, v199
	v_cvt_pk_u8_f32 v196, v121, 3, v196
	v_cvt_pk_u8_f32 v197, v125, 3, v197
	v_cvt_pk_u8_f32 v198, v129, 3, v198
	v_cvt_pk_u8_f32 v199, v133, 3, v199
	v_cvt_pk_u8_f32 v200, v180, 0, 0
	v_cvt_pk_u8_f32 v201, v184, 0, 0
	v_cvt_pk_u8_f32 v202, v188, 0, 0
	v_cvt_pk_u8_f32 v203, v192, 0, 0
	s_waitcnt lgkmcnt(8)
	v_mfma_f32_32x32x64_f8f6f4 v[102:117], v[212:219], v[146:153], v[50:65]
	v_cvt_pk_u8_f32 v200, v181, 1, v200
	v_cvt_pk_u8_f32 v201, v185, 1, v201
	v_cvt_pk_u8_f32 v202, v189, 1, v202
	v_cvt_pk_u8_f32 v203, v193, 1, v203
	v_cvt_pk_u8_f32 v200, v182, 2, v200
	v_cvt_pk_u8_f32 v201, v186, 2, v201
	v_cvt_pk_u8_f32 v202, v190, 2, v202
	v_cvt_pk_u8_f32 v203, v194, 2, v203
	v_cvt_pk_u8_f32 v200, v183, 3, v200
	v_cvt_pk_u8_f32 v201, v187, 3, v201
	v_cvt_pk_u8_f32 v202, v191, 3, v202
	v_cvt_pk_u8_f32 v203, v195, 3, v203
	s_nop 0
	s_waitcnt lgkmcnt(0)
	s_barrier
	v_mfma_f32_32x32x64_f8f6f4 v[66:81], v[220:227], v[196:203], v[66:81] blgp:1
	ds_read_b128 v[204:207], v179 offset:4096
	ds_read_b128 v[208:211], v179 offset:5120
	ds_read_b128 v[212:215], v179 offset:6144
	ds_read_b128 v[216:219], v179 offset:7168
	s_cbranch_vccz .Ldma_dif0_skip0
	s_mul_i32 s101, s55, 0x6000
	s_add_i32 s101, s101, s22
	s_mov_b32 m0, s101
	s_nop 0
	global_load_lds_dwordx4 v164, s[62:63]

.Lback_dif0_3:
	v_cvt_pk_u8_f32 v196, v86, 0, 0
	v_cvt_pk_u8_f32 v197, v90, 0, 0
	v_cvt_pk_u8_f32 v198, v94, 0, 0
	v_cvt_pk_u8_f32 v199, v98, 0, 0
	v_cvt_pk_u8_f32 v196, v87, 1, v196
	v_cvt_pk_u8_f32 v197, v91, 1, v197
	v_cvt_pk_u8_f32 v198, v95, 1, v198
	v_cvt_pk_u8_f32 v199, v99, 1, v199
	s_waitcnt lgkmcnt(8)
	v_mfma_f32_32x32x64_f8f6f4 v[118:133], v[204:211], v[146:153], v[50:65]
	v_cvt_pk_u8_f32 v196, v88, 2, v196
	v_cvt_pk_u8_f32 v197, v92, 2, v197
	v_cvt_pk_u8_f32 v198, v96, 2, v198
	v_cvt_pk_u8_f32 v199, v100, 2, v199
	v_cvt_pk_u8_f32 v196, v89, 3, v196
	v_cvt_pk_u8_f32 v197, v93, 3, v197
	v_cvt_pk_u8_f32 v198, v97, 3, v198
	v_cvt_pk_u8_f32 v199, v101, 3, v199
	v_cvt_pk_u8_f32 v200, v102, 0, 0
	v_cvt_pk_u8_f32 v201, v106, 0, 0
	v_cvt_pk_u8_f32 v202, v110, 0, 0
	v_cvt_pk_u8_f32 v203, v114, 0, 0
	v_mfma_f32_32x32x64_f8f6f4 v[180:195], v[212:219], v[146:153], v[50:65]
	v_cvt_pk_u8_f32 v200, v103, 1, v200
	v_cvt_pk_u8_f32 v201, v107, 1, v201
	v_cvt_pk_u8_f32 v202, v111, 1, v202
	v_cvt_pk_u8_f32 v203, v115, 1, v203
	v_cvt_pk_u8_f32 v200, v104, 2, v200
	v_cvt_pk_u8_f32 v201, v108, 2, v201
	v_cvt_pk_u8_f32 v202, v112, 2, v202
	v_cvt_pk_u8_f32 v203, v116, 2, v203
	v_cvt_pk_u8_f32 v200, v105, 3, v200
	v_cvt_pk_u8_f32 v201, v109, 3, v201
	v_cvt_pk_u8_f32 v202, v113, 3, v202
	v_cvt_pk_u8_f32 v203, v117, 3, v203
	s_nop 0
	s_waitcnt lgkmcnt(0)
	v_mfma_f32_32x32x64_f8f6f4 v[66:81], v[220:227], v[196:203], v[66:81] blgp:1
	v_mfma_f32_32x32x64_f8f6f4 v[34:49], v[228:235], v[196:203], v[34:49] blgp:1
	ds_read_b128 v[220:223], v179 offset:40960
	ds_read_b128 v[224:227], v179 offset:41984
	v_mfma_f32_32x32x64_f8f6f4 v[18:33], v[236:243], v[196:203], v[18:33] blgp:1
	ds_read_b128 v[228:231], v179 offset:43008
	ds_read_b128 v[232:235], v179 offset:44032
	v_max3_f32 v134, v118, v119, v120
	v_max3_f32 v134, v134, v121, v122
	v_max3_f32 v134, v134, v123, v124
	v_max3_f32 v134, v134, v125, v126
	v_max3_f32 v134, v134, v127, v128
	v_max3_f32 v134, v134, v129, v130
	v_max3_f32 v134, v134, v131, v132
	v_max3_f32 v134, v134, v133, v133
	v_mfma_f32_32x32x64_f8f6f4 v[2:17], v[244:251], v[196:203], v[2:17] blgp:1
	ds_read_b128 v[236:239], v179 offset:45056
	ds_read_b128 v[240:243], v179 offset:46080
	v_max3_f32 v134, v134, v180, v181
	v_max3_f32 v134, v134, v182, v183
	v_max3_f32 v134, v134, v184, v185
	v_max3_f32 v134, v134, v186, v187
	v_max3_f32 v134, v134, v188, v189
	v_max3_f32 v134, v134, v190, v191
	v_max3_f32 v134, v134, v192, v193
	v_max3_f32 v134, v134, v194, v195
	v_cmp_gt_f32_e64 s[98:99], v134, v178
	v_mfma_f32_16x16x128_f8f6f4 v[82:85], v[154:161], v[196:203], v[82:85] blgp:1
	s_waitcnt vmcnt(0)
	s_barrier
	ds_read_b128 v[204:207], v135
	ds_read_b128 v[208:211], v135 offset:1024
	ds_read_b128 v[212:215], v135 offset:2048
	ds_read_b128 v[216:219], v135 offset:3072
	ds_read_b128 v[244:247], v179 offset:47104
	ds_read_b128 v[248:251], v179 offset:48128
	s_cbranch_vccnz .LBB0_1300
	s_waitcnt lgkmcnt(0)
	s_cmp_lg_u64 s[98:99], 0
	s_cbranch_scc1 .Lslow_dif0_4

.LBB0_4060:
	s_lshl_b32 s4, s44, 5
	s_lshr_b32 s2, s44, 1
	s_and_b32 s4, s4, 32
	s_ashr_i32 s0, s12, 6
	s_and_b32 s1, s12, 63
	s_add_i32 s2, s2, s34
	s_add_i32 s4, s4, s31
	s_and_b64 s[12:13], s[18:19], exec
	s_cselect_b32 s0, s2, s0
	s_cselect_b32 s1, s4, s1
	s_lshr_b32 s2, s0, 3
	s_mulk_i32 s2, 0x4100
	s_lshl_b32 s1, s1, 8
	s_and_b32 s4, s0, 7
	s_add_i32 s2, s2, s1
	v_add_u32_e32 v166, s2, v170
	s_lshl_b32 s24, s4, 7
	s_lshl_b32 s12, s4, 2
	s_mul_i32 s46, s0, 0x208000
	v_ashrrev_i32_e32 v167, 31, v166
	s_mul_hi_i32 s47, s0, 0x208000
	s_add_u32 s1, s35, s46
	v_lshlrev_b64 v[4:5], 5, v[166:167]
	s_addc_u32 s2, s36, s47
	s_mul_i32 s55, s0, 0x104000
	v_lshl_add_u64 v[4:5], s[16:17], 0, v[4:5]
	s_mov_b32 s13, s25
	s_mul_hi_i32 s64, s0, 0x104000
	s_add_u32 s4, s37, s55
	v_lshl_add_u64 v[4:5], v[4:5], 0, s[12:13]
	s_addc_u32 s5, s38, s64
	s_add_i32 s12, s0, 32
	v_lshlrev_b64 v[2:3], 10, v[166:167]
	s_ashr_i32 s13, s12, 31
	v_lshl_add_u64 v[2:3], s[22:23], 0, v[2:3]
	s_lshl_b64 s[12:13], s[12:13], 2
	v_lshl_add_u64 v[2:3], v[2:3], 0, s[24:25]
	s_add_u32 s12, s3, s12
	s_addc_u32 s13, s30, s13
	v_lshl_add_u64 v[2:3], v[2:3], 0, v[178:179]
	global_load_dword v58, v[4:5], off
	global_load_dword v50, v163, s[12:13]
	global_load_dwordx4 v[142:145], v[2:3], off offset:16
	global_load_dwordx4 v[138:141], v[2:3], off
	global_load_dwordx4 v[150:153], v[2:3], off offset:80
	global_load_dwordx4 v[146:149], v[2:3], off offset:64
	v_readfirstlane_b32 s0, v1
	s_ashr_i32 s0, s0, 6
	s_cmp_lt_i32 s0, 6
	s_mul_i32 s48, s0, 0xc00
	s_cselect_b64 s[14:15], -1, 0
	s_add_i32 s65, s48, 0xffffc000
	s_add_u32 s6, s4, s65
	s_addc_u32 s7, s5, 0
	s_ashr_i32 s49, s48, 31
	s_add_u32 s8, s1, s48
	s_addc_u32 s9, s2, s49
	s_and_b64 s[12:13], s[14:15], exec
	s_cselect_b32 s13, s9, s7
	s_cselect_b32 s12, s8, s6
	s_add_i32 s45, s48, 0
	s_cmp_lt_i32 s0, 5
	s_cselect_b64 s[28:29], -1, 0
	s_add_i32 s0, s48, 0x400
	s_ashr_i32 s6, s0, 31
	s_add_u32 s7, s8, 0x400
	s_addc_u32 s10, s9, 0
	s_add_i32 s52, s48, 0xffffc400
	s_add_u32 s11, s4, s52
	s_addc_u32 s33, s5, 0
	v_lshl_add_u64 v[2:3], s[12:13], 0, v[164:165]
	s_and_b64 s[12:13], s[28:29], exec
	s_mov_b32 m0, s45
	s_cselect_b32 s13, s10, s33
	s_cselect_b32 s12, s7, s11
	s_add_i32 s7, s48, 0x800
	v_lshrrev_b32 v154, 2, v0
	v_xor_b32 v154, v154, v0
	v_bfe_u32 v154, v154, 2, 1
	v_add_u32 v154, -1, v154
	v_and_b32 v154, 0x38383838, v154
	v_mov_b32 v155, v154
	v_mov_b32 v156, v154
	v_mov_b32 v157, v154
	v_mov_b32 v158, v154
	v_mov_b32 v159, v154
	v_mov_b32 v160, v154
	v_mov_b32 v161, v154
	global_load_lds_dwordx4 v[2:3], off
	s_add_i32 m0, s45, 0x400
	s_ashr_i32 s10, s7, 31
	s_add_u32 s8, s8, 0x800
	s_addc_u32 s9, s9, 0
	s_add_i32 s53, s48, 0xffffc800
	s_add_u32 s11, s4, s53
	s_addc_u32 s33, s5, 0
	v_lshl_add_u64 v[2:3], s[12:13], 0, v[164:165]
	s_and_b64 s[12:13], s[28:29], exec
	global_load_lds_dwordx4 v[2:3], off
	s_cselect_b32 s13, s9, s33
	s_cselect_b32 s12, s8, s11
	s_add_i32 m0, s45, 0x800
	s_add_u32 s4, s4, 0x2000
	s_addc_u32 s5, s5, 0
	s_add_u32 s1, s1, 0x4000
	s_addc_u32 s2, s2, 0
	s_add_u32 s8, s1, s48
	s_addc_u32 s9, s2, s49
	s_add_u32 s11, s4, s65
	s_addc_u32 s33, s5, 0
	v_lshl_add_u64 v[2:3], s[12:13], 0, v[164:165]
	s_and_b64 s[12:13], s[14:15], exec
	global_load_lds_dwordx4 v[2:3], off
	s_cselect_b32 s13, s9, s33
	s_cselect_b32 s12, s8, s11
	s_add_i32 m0, s45, 0x6000
	s_add_u32 s0, s1, s0
	s_addc_u32 s6, s2, s6
	s_add_u32 s8, s4, s52
	s_addc_u32 s9, s5, 0
	v_lshl_add_u64 v[2:3], s[12:13], 0, v[164:165]
	s_and_b64 s[12:13], s[28:29], exec
	global_load_lds_dwordx4 v[2:3], off
	s_cselect_b32 s13, s6, s9
	s_cselect_b32 s12, s0, s8
	s_add_i32 m0, s45, 0x6400
	s_add_u32 s0, s1, s7
	s_addc_u32 s1, s2, s10
	s_add_u32 s2, s4, s53
	s_addc_u32 s4, s5, 0
	v_lshl_add_u64 v[2:3], s[12:13], 0, v[164:165]
	s_and_b64 s[12:13], s[28:29], exec
	s_cselect_b32 s13, s1, s4
	s_cselect_b32 s12, s0, s2
	global_load_lds_dwordx4 v[2:3], off
	v_lshl_add_u64 v[2:3], s[12:13], 0, v[164:165]
	s_add_i32 m0, s45, 0x6800
	s_waitcnt vmcnt(0)
	v_mul_f32_e32 v51, 0x4f800000, v50
	global_load_lds_dwordx4 v[2:3], off
	s_waitcnt vmcnt(3)
	s_barrier
	ds_read_b128 v[2:5], v171
	ds_read_b128 v[6:9], v171 offset:1024
	s_waitcnt lgkmcnt(0)
	v_mfma_f32_32x32x64_f8f6f4 v[2:17], v[2:9], v[138:145], 0
	ds_read_b128 v[18:21], v171 offset:2048
	ds_read_b128 v[22:25], v171 offset:3072
	v_cmp_gt_f32_e32 vcc, s39, v50
	s_add_u32 s46, s46, s48
	s_addc_u32 s47, s47, s49
	v_cndmask_b32_e32 v59, v50, v51, vcc
	v_sqrt_f32_e32 v60, v59
	s_add_u32 s48, s55, s53
	s_addc_u32 s49, s64, 0
	s_add_u32 s52, s55, s52
	v_add_u32_e32 v61, -1, v60
	v_fma_f32 v62, -v61, v60, v59
	v_cmp_ge_f32_e64 s[12:13], 0, v62
	v_add_u32_e32 v62, 1, v60
	s_addc_u32 s53, s64, 0
	v_cndmask_b32_e64 v61, v60, v61, s[12:13]
	s_waitcnt lgkmcnt(0)
	v_mfma_f32_32x32x64_f8f6f4 v[2:17], v[18:25], v[146:153], v[2:17]
	ds_read_b128 v[18:21], v171 offset:4096
	ds_read_b128 v[22:25], v171 offset:5120
	ds_read_b128 v[34:37], v171 offset:6144
	ds_read_b128 v[38:41], v171 offset:7168
	v_fma_f32 v60, -v62, v60, v59
	v_cmp_lt_f32_e64 s[12:13], 0, v60
	s_add_u32 s55, s55, s65
	s_addc_u32 s64, s64, 0
	v_cndmask_b32_e64 v60, v61, v62, s[12:13]
	s_mov_b32 s67, 0
	s_mov_b32 s65, 0
	v_mov_b32_e32 v61, v163
	v_mov_b32_e32 v62, v163
	v_mov_b32_e32 v63, v163
	v_mov_b32_e32 v64, v163
	v_mov_b32_e32 v65, v163
	s_nop 3
	v_max3_f32 v2, v2, s41, v3
	s_waitcnt lgkmcnt(0)
	v_mfma_f32_32x32x64_f8f6f4 v[18:33], v[18:25], v[138:145], 0
	v_max3_f32 v2, v2, v4, v5
	v_max3_f32 v2, v2, v6, v7
	v_max3_f32 v2, v2, v8, v9
	v_max3_f32 v2, v2, v10, v11
	v_max3_f32 v2, v2, v12, v13
	v_max3_f32 v2, v2, v14, v15
	v_max3_f32 v2, v2, v16, v17
	v_mfma_f32_32x32x64_f8f6f4 v[18:33], v[34:41], v[146:153], v[18:33]
	ds_read_b128 v[34:37], v171 offset:8192
	ds_read_b128 v[38:41], v171 offset:9216
	ds_read_b128 v[50:53], v171 offset:10240
	ds_read_b128 v[54:57], v171 offset:11264
	s_waitcnt lgkmcnt(0)
	v_mfma_f32_32x32x64_f8f6f4 v[34:49], v[34:41], v[138:145], 0
	s_nop 13
	v_max3_f32 v2, v2, v18, v19
	v_max3_f32 v2, v2, v20, v21
	v_max3_f32 v18, v2, v22, v23
	v_max3_f32 v18, v18, v24, v25
	v_max3_f32 v18, v18, v26, v27
	v_max3_f32 v18, v18, v28, v29
	v_max3_f32 v18, v18, v30, v31
	v_max3_f32 v26, v18, v32, v33
	v_mov_b32_e32 v27, v163
	v_mov_b32_e32 v28, v163
	v_mov_b32_e32 v29, v163
	v_mov_b32_e32 v30, v163
	v_mov_b32_e32 v31, v163
	v_mov_b32_e32 v32, v163
	v_mov_b32_e32 v33, v163
	v_mfma_f32_32x32x64_f8f6f4 v[34:49], v[50:57], v[146:153], v[34:49]
	v_mul_f32_e32 v50, 0x37800000, v60
	v_cndmask_b32_e32 v60, v60, v50, vcc
	ds_read_b128 v[50:53], v171 offset:12288
	ds_read_b128 v[54:57], v171 offset:13312
	ds_read_b128 v[18:21], v171 offset:14336
	ds_read_b128 v[22:25], v171 offset:15360
	v_cmp_lt_i32_e32 vcc, v176, v177
	s_nop 12
	v_max3_f32 v26, v26, v34, v35
	s_waitcnt lgkmcnt(0)
	v_mfma_f32_32x32x64_f8f6f4 v[2:17], v[50:57], v[138:145], 0
	v_max3_f32 v26, v26, v36, v37
	v_max3_f32 v26, v26, v38, v39
	v_max3_f32 v26, v26, v40, v41
	v_max3_f32 v26, v26, v42, v43
	v_max3_f32 v26, v26, v44, v45
	v_max3_f32 v26, v26, v46, v47
	v_max3_f32 v26, v26, v48, v49
	v_mov_b32_e32 v50, 0
	v_mov_b32_e32 v51, v163
	v_mov_b32_e32 v52, v163
	v_mov_b32_e32 v53, v163
	v_mov_b32_e32 v54, v163
	v_mov_b32_e32 v55, v163
	v_mov_b32_e32 v56, v163
	v_mov_b32_e32 v57, v163
	v_mfma_f32_32x32x64_f8f6f4 v[2:17], v[18:25], v[146:153], v[2:17]
	v_mov_b32_e32 v18, 0
	v_mov_b32_e32 v19, v163
	v_mov_b32_e32 v20, v163
	v_mov_b32_e32 v21, v163
	v_mov_b32_e32 v22, v163
	v_mov_b32_e32 v23, v163
	v_mov_b32_e32 v24, v163
	v_mov_b32_e32 v25, v163
	s_nop 11
	v_max3_f32 v2, v26, v2, v3
	v_max3_f32 v2, v2, v4, v5
	v_max3_f32 v2, v2, v6, v7
	v_max3_f32 v2, v2, v8, v9
	v_max3_f32 v2, v2, v10, v11
	v_max3_f32 v2, v2, v12, v13
	v_max3_f32 v2, v2, v14, v15
	v_cndmask_b32_e32 v3, v175, v176, vcc
	v_max3_f32 v2, v2, v16, v17
	v_lshlrev_b32_e32 v3, 2, v3
	ds_bpermute_b32 v3, v3, v2
	v_cmp_class_f32_e32 vcc, v59, v172
	v_mov_b32_e32 v26, v163
	v_mov_b32_e32 v5, v163
	v_cndmask_b32_e32 v4, v60, v59, vcc
	s_waitcnt lgkmcnt(0)
	v_max_f32_e32 v3, v3, v3
	v_mul_f32_e32 v4, v58, v4
	v_max_f32_e32 v2, v2, v3
	v_fmamk_f32 v4, v4, 0x3f90a3d7, v173
	v_add_f32_e32 v2, 0x42800000, v2
	v_min_f32_e32 v2, v4, v2
	v_add_f32_e32 v2, 0xc2ec0000, v2
	v_xor_b32_e32 v34, 0x80000000, v2
	v_mov_b32_e32 v35, v34
	v_mov_b32_e32 v36, v34
	v_mov_b32_e32 v37, v34
	v_mov_b32_e32 v38, v34
	v_mov_b32_e32 v39, v34
	v_mov_b32_e32 v40, v34
	v_mov_b32_e32 v41, v34
	v_mov_b32_e32 v42, v34
	v_mov_b32_e32 v43, v34
	v_mov_b32_e32 v44, v34
	v_mov_b32_e32 v45, v34
	v_mov_b32_e32 v46, v34
	v_mov_b32_e32 v47, v34
	v_mov_b32_e32 v48, v34
	v_mov_b32_e32 v49, v34
	v_mov_b32_e32 v58, v163
	v_mov_b32_e32 v59, v163
	v_mov_b32_e32 v60, v163
	v_mov_b32_e32 v2, 0
	v_mov_b32_e32 v3, v163
	v_mov_b32_e32 v4, v163
	v_mov_b32_e32 v6, v163
	v_mov_b32_e32 v7, v163
	v_mov_b32_e32 v8, v163
	v_mov_b32_e32 v9, v163
	v_mov_b32_e32 v10, v163
	v_mov_b32_e32 v11, v163
	v_mov_b32_e32 v12, v163
	v_mov_b32_e32 v13, v163
	v_mov_b32_e32 v14, v163
	v_mov_b32_e32 v15, v163
	v_mov_b32_e32 v16, v163
	v_mov_b32_e32 v17, v163
	v_mov_b32_e32 v86, v163
	v_mov_b32_e32 v87, v163
	v_mov_b32_e32 v88, v163
	v_mov_b32_e32 v89, v163
	v_mov_b32_e32 v90, v163
	v_mov_b32_e32 v91, v163
	v_mov_b32_e32 v92, v163
	v_mov_b32_e32 v93, v163
	v_mov_b32_e32 v94, v163
	v_mov_b32_e32 v95, v163
	v_mov_b32_e32 v96, v163
	v_mov_b32_e32 v97, v163
	v_mov_b32_e32 v98, v163
	v_mov_b32_e32 v99, v163
	v_mov_b32_e32 v100, v163
	v_mov_b32_e32 v101, v163
	v_mov_b32_e32 v102, v163
	v_mov_b32_e32 v103, v163
	v_mov_b32_e32 v104, v163
	v_mov_b32_e32 v105, v163
	v_mov_b32_e32 v106, v163
	v_mov_b32_e32 v107, v163
	v_mov_b32_e32 v108, v163
	v_mov_b32_e32 v109, v163
	v_mov_b32_e32 v110, v163
	v_mov_b32_e32 v111, v163
	v_mov_b32_e32 v112, v163
	v_mov_b32_e32 v113, v163
	v_mov_b32_e32 v114, v163
	v_mov_b32_e32 v115, v163
	v_mov_b32_e32 v116, v163
	v_mov_b32_e32 v117, v163
	v_mov_b32_e32 v228, v163
	v_mov_b32_e32 v229, v163
	v_mov_b32_e32 v230, v163
	v_mov_b32_e32 v231, v163
	v_mov_b32_e32 v232, v163
	v_mov_b32_e32 v233, v163
	v_mov_b32_e32 v234, v163
	v_mov_b32_e32 v235, v163
	v_mov_b32_e32 v236, v163
	v_mov_b32_e32 v237, v163
	v_mov_b32_e32 v238, v163
	v_mov_b32_e32 v239, v163
	v_mov_b32_e32 v240, v163
	v_mov_b32_e32 v241, v163
	v_mov_b32_e32 v242, v163
	v_mov_b32_e32 v243, v163
	s_add_u32 s98, s20, s46
	s_addc_u32 s99, s21, s47
	s_add_u32 s98, s98, 0x23076100
	s_addc_u32 s99, s99, 0
	s_add_u32 s100, s20, s55
	s_addc_u32 s101, s21, s64
	s_add_u32 s100, s100, 0x26132100
	s_addc_u32 s101, s101, 0
	s_movk_i32 s2, 0x2000
	s_and_b64 s[0:1], s[14:15], exec
	s_cselect_b32 s1, s99, s101
	s_cselect_b32 s0, s98, s100
	s_cselect_b32 s2, 0x4000, s2
	s_add_u32 s8, s0, s2
	s_addc_u32 s9, s1, 0
	s_lshl_b32 s2, s2, 1
	s_add_u32 s98, s20, s46
	s_addc_u32 s99, s21, s47
	s_add_u32 s98, s98, 0x23076500
	s_addc_u32 s99, s99, 0
	s_add_u32 s100, s20, s52
	s_addc_u32 s101, s21, s53
	s_add_u32 s100, s100, 0x26132100
	s_addc_u32 s101, s101, 0
	s_movk_i32 s33, 0x2000
	s_and_b64 s[4:5], s[28:29], exec
	s_cselect_b32 s5, s99, s101
	s_cselect_b32 s4, s98, s100
	s_cselect_b32 s33, 0x4000, s33
	s_add_u32 s10, s4, s33
	s_addc_u32 s11, s5, 0
	s_lshl_b32 s33, s33, 1
	s_add_u32 s98, s20, s46
	s_addc_u32 s99, s21, s47
	s_add_u32 s98, s98, 0x23076900
	s_addc_u32 s99, s99, 0
	s_add_u32 s100, s20, s48
	s_addc_u32 s101, s21, s49
	s_add_u32 s100, s100, 0x26132100
	s_addc_u32 s101, s101, 0
	s_movk_i32 s50, 0x2000
	s_and_b64 s[6:7], s[28:29], exec
	s_cselect_b32 s7, s99, s101
	s_cselect_b32 s6, s98, s100
	s_cselect_b32 s50, 0x4000, s50
	s_add_u32 s68, s6, s50
	s_addc_u32 s69, s7, 0
	s_lshl_b32 s50, s50, 1
	s_mov_b64 s[98:99], 0
	v_mov_b32_e32 v167, v171
	v_add_u32_e32 v127, 0xc000, v171
	s_waitcnt vmcnt(0) lgkmcnt(0)
	s_barrier
	ds_read_b128 v[190:193], v167
	ds_read_b128 v[194:197], v167 offset:1024
	ds_read_b128 v[198:201], v167 offset:2048
	ds_read_b128 v[202:205], v167 offset:3072
	ds_read_b128 v[206:209], v167 offset:4096
	ds_read_b128 v[210:213], v167 offset:5120
	ds_read_b128 v[220:223], v167 offset:6144
	ds_read_b128 v[224:227], v167 offset:7168
	s_waitcnt lgkmcnt(0)
	s_branch .LBB0_4061

.LBB0_4061:
	s_cmpk_gt_u32 s65, 0x7f
	s_cselect_b64 vcc, 0, exec
	s_add_i32 s65, s65, 2
	s_xor_b32 s67, s67, 2
	s_cmp_lg_u64 s[98:99], 0
	s_cbranch_scc1 .Lslow_mla1_0
.Lback_mla1_0:
	v_cvt_pk_u8_f32 v118, v86, 0, 0
	v_cvt_pk_u8_f32 v119, v90, 0, 0
	v_cvt_pk_u8_f32 v120, v94, 0, 0
	v_cvt_pk_u8_f32 v121, v98, 0, 0
	v_cvt_pk_u8_f32 v118, v87, 1, v118
	v_cvt_pk_u8_f32 v119, v91, 1, v119
	v_cvt_pk_u8_f32 v120, v95, 1, v120
	v_cvt_pk_u8_f32 v121, v99, 1, v121
	s_waitcnt lgkmcnt(10)
	v_mfma_f32_32x32x64_f8f6f4 v[54:69], v[190:197], v[138:145], v[34:49]
	v_cvt_pk_u8_f32 v118, v88, 2, v118
	v_cvt_pk_u8_f32 v119, v92, 2, v119
	v_cvt_pk_u8_f32 v120, v96, 2, v120
	v_cvt_pk_u8_f32 v121, v100, 2, v121
	v_cvt_pk_u8_f32 v118, v89, 3, v118
	v_cvt_pk_u8_f32 v119, v93, 3, v119
	v_cvt_pk_u8_f32 v120, v97, 3, v120
	v_cvt_pk_u8_f32 v121, v101, 3, v121
	s_waitcnt lgkmcnt(8)
	v_mfma_f32_32x32x64_f8f6f4 v[54:69], v[198:205], v[146:153], v[54:69]
	v_cvt_pk_u8_f32 v122, v102, 0, 0
	v_cvt_pk_u8_f32 v123, v106, 0, 0
	v_cvt_pk_u8_f32 v124, v110, 0, 0
	v_cvt_pk_u8_f32 v125, v114, 0, 0
	v_cvt_pk_u8_f32 v122, v103, 1, v122
	v_cvt_pk_u8_f32 v123, v107, 1, v123
	v_cvt_pk_u8_f32 v124, v111, 1, v124
	v_cvt_pk_u8_f32 v125, v115, 1, v125
	s_waitcnt lgkmcnt(6)
	v_mfma_f32_32x32x64_f8f6f4 v[70:85], v[206:213], v[138:145], v[34:49]
	v_cvt_pk_u8_f32 v122, v104, 2, v122
	v_cvt_pk_u8_f32 v123, v108, 2, v123
	v_cvt_pk_u8_f32 v124, v112, 2, v124
	v_cvt_pk_u8_f32 v125, v116, 2, v125
	v_cvt_pk_u8_f32 v122, v105, 3, v122
	v_cvt_pk_u8_f32 v123, v109, 3, v123
	v_cvt_pk_u8_f32 v124, v113, 3, v124
	v_cvt_pk_u8_f32 v125, v117, 3, v125
	s_waitcnt lgkmcnt(4)
	v_mfma_f32_32x32x64_f8f6f4 v[70:85], v[220:227], v[146:153], v[70:85]
	s_nop 0
	s_waitcnt lgkmcnt(0)
	s_barrier
	v_mfma_f32_32x32x64_f8f6f4 v[18:33], v[228:235], v[118:125], v[18:33] blgp:1
	ds_read_b128 v[190:193], v167 offset:8192
	ds_read_b128 v[194:197], v167 offset:9216
	ds_read_b128 v[198:201], v167 offset:10240
	ds_read_b128 v[202:205], v167 offset:11264
	s_cbranch_vccz .Ldma_mla1_skip0
	s_mul_i32 s101, s67, 0x6000
	s_add_i32 s101, s101, s45
	s_mov_b32 m0, s101
	s_nop 0
	global_load_lds_dwordx4 v164, s[0:1]

.LBB0_4070:
	s_lshl_b32 s4, s42, 5
	s_lshr_b32 s2, s42, 1
	s_and_b32 s4, s4, 32
	s_ashr_i32 s0, s12, 6
	s_and_b32 s1, s12, 63
	s_add_i32 s2, s2, s34
	s_add_i32 s4, s4, s31
	s_and_b64 s[12:13], s[18:19], exec
	s_cselect_b32 s0, s2, s0
	s_cselect_b32 s1, s4, s1
	s_ashr_i32 s2, s0, 3
	s_mul_i32 s4, s2, 0x4100
	s_lshl_b32 s1, s1, 8
	s_add_i32 s4, s4, s1
	v_add_u32_e32 v166, s4, v170
	v_ashrrev_i32_e32 v167, 31, v166
	s_and_b32 s43, s0, 7
	v_lshlrev_b64 v[2:3], 9, v[166:167]
	v_lshl_add_u64 v[2:3], s[20:21], 0, v[2:3]
	s_lshl_b32 s24, s43, 6
	v_lshl_add_u64 v[2:3], v[2:3], 0, s[24:25]
	s_lshl_b32 s24, s43, 2
	s_mul_i32 s44, s0, 0x104000
	s_mul_hi_i32 s45, s0, 0x104000
	s_add_u32 s1, s35, s44
	s_addc_u32 s4, s36, s45
	s_lshl_b32 s2, s2, 2
	s_bfe_u32 s5, s0, 0x20001
	s_or_b32 s52, s2, s5
	s_mul_hi_i32 s53, s52, 0x208000
	s_mul_i32 s52, s52, 0x208000
	s_add_u32 s2, s37, s52
	s_addc_u32 s5, s38, s53
	s_add_i32 s12, s0, 16
	s_ashr_i32 s13, s12, 31
	v_lshlrev_b64 v[4:5], 5, v[166:167]
	s_lshl_b64 s[12:13], s[12:13], 2
	v_lshl_add_u64 v[4:5], s[16:17], 0, v[4:5]
	s_add_u32 s12, s3, s12
	v_lshl_add_u64 v[4:5], v[4:5], 0, s[24:25]
	s_addc_u32 s13, s28, s13
	global_load_dword v42, v[4:5], off
	global_load_dword v18, v163, s[12:13]
	v_lshl_add_u64 v[2:3], v[2:3], 0, v[210:211]
	global_load_dwordx4 v[150:153], v[2:3], off offset:16
	global_load_dwordx4 v[146:149], v[2:3], off
	v_readfirstlane_b32 s0, v1
	s_ashr_i32 s0, s0, 6
	s_cmp_lt_i32 s0, 3
	s_mul_i32 s46, s0, 0xc00
	s_cselect_b64 s[14:15], -1, 0
	s_add_i32 s55, s46, 0xffffe000
	s_add_u32 s6, s2, s55
	s_addc_u32 s7, s5, 0
	s_ashr_i32 s47, s46, 31
	s_add_u32 s8, s1, s46
	s_addc_u32 s9, s4, s47
	s_and_b64 s[12:13], s[14:15], exec
	s_cselect_b32 s13, s9, s7
	s_cselect_b32 s12, s8, s6
	s_add_i32 s6, s46, 0x400
	s_add_i32 s24, s46, 0
	s_ashr_i32 s7, s6, 31
	s_add_u32 s10, s8, 0x400
	s_addc_u32 s11, s9, 0
	s_add_i32 s48, s46, 0xffffe400
	s_add_u32 s26, s2, s48
	s_addc_u32 s27, s5, 0
	v_lshl_add_u64 v[2:3], s[12:13], 0, v[164:165]
	s_mov_b32 m0, s24
	s_and_b64 s[12:13], s[14:15], exec
	v_lshrrev_b32 v154, 2, v0
	v_xor_b32 v154, v154, v0
	v_bfe_u32 v154, v154, 2, 1
	v_add_u32 v154, -1, v154
	v_and_b32 v154, 0x38383838, v154
	v_mov_b32 v155, v154
	v_mov_b32 v156, v154
	v_mov_b32 v157, v154
	v_mov_b32 v158, v154
	v_mov_b32 v159, v154
	v_mov_b32 v160, v154
	v_mov_b32 v161, v154
	global_load_lds_dwordx4 v[2:3], off
	s_cselect_b32 s13, s11, s27
	s_cselect_b32 s12, s10, s26
	s_add_i32 m0, s24, 0x400
	s_cmp_lt_i32 s0, 2
	s_cselect_b64 s[26:27], -1, 0
	s_add_i32 s0, s46, 0x800
	s_ashr_i32 s10, s0, 31
	s_add_u32 s8, s8, 0x800
	s_addc_u32 s9, s9, 0
	s_add_i32 s49, s46, 0xffffe800
	s_add_u32 s11, s2, s49
	s_addc_u32 s33, s5, 0
	v_lshl_add_u64 v[2:3], s[12:13], 0, v[164:165]
	s_and_b64 s[12:13], s[26:27], exec
	global_load_lds_dwordx4 v[2:3], off
	s_cselect_b32 s13, s9, s33
	s_cselect_b32 s12, s8, s11
	s_add_i32 m0, s24, 0x800
	s_add_u32 s2, s2, 0x4000
	s_addc_u32 s5, s5, 0
	s_add_u32 s1, s1, 0x2000
	s_addc_u32 s4, s4, 0
	s_add_u32 s8, s1, s46
	s_addc_u32 s9, s4, s47
	s_add_u32 s11, s2, s55
	s_addc_u32 s33, s5, 0
	v_lshl_add_u64 v[2:3], s[12:13], 0, v[164:165]
	s_and_b64 s[12:13], s[14:15], exec
	global_load_lds_dwordx4 v[2:3], off
	s_cselect_b32 s13, s9, s33
	s_cselect_b32 s12, s8, s11
	s_add_i32 m0, s24, 0x6000
	s_add_u32 s6, s1, s6
	s_addc_u32 s7, s4, s7
	s_add_u32 s8, s2, s48
	s_addc_u32 s9, s5, 0
	v_lshl_add_u64 v[2:3], s[12:13], 0, v[164:165]
	s_and_b64 s[12:13], s[14:15], exec
	global_load_lds_dwordx4 v[2:3], off
	s_cselect_b32 s13, s7, s9
	s_cselect_b32 s12, s6, s8
	s_add_i32 m0, s24, 0x6400
	s_add_u32 s0, s1, s0
	s_addc_u32 s1, s4, s10
	s_add_u32 s2, s2, s49
	s_addc_u32 s4, s5, 0
	v_lshl_add_u64 v[2:3], s[12:13], 0, v[164:165]
	s_and_b64 s[12:13], s[26:27], exec
	s_cselect_b32 s13, s1, s4
	s_cselect_b32 s12, s0, s2
	global_load_lds_dwordx4 v[2:3], off
	v_lshl_add_u64 v[2:3], s[12:13], 0, v[164:165]
	s_add_i32 m0, s24, 0x6800
	s_waitcnt vmcnt(0)
	v_mul_f32_e32 v19, 0x4f800000, v18
	global_load_lds_dwordx4 v[2:3], off
	s_waitcnt vmcnt(3)
	s_barrier
	ds_read_b128 v[2:5], v171
	ds_read_b128 v[6:9], v171 offset:1024
	v_cmp_gt_f32_e32 vcc, s39, v18
	s_waitcnt lgkmcnt(0)
	v_mfma_f32_32x32x64_f8f6f4 v[2:17], v[2:9], v[146:153], 0
	v_cndmask_b32_e32 v43, v18, v19, vcc
	v_sqrt_f32_e32 v26, v43
	ds_read_b128 v[18:21], v171 offset:2048
	ds_read_b128 v[22:25], v171 offset:3072
	s_add_u32 s44, s44, s46
	s_addc_u32 s45, s45, s47
	v_add_u32_e32 v27, -1, v26
	v_fma_f32 v28, -v27, v26, v43
	v_cmp_ge_f32_e64 s[12:13], 0, v28
	v_add_u32_e32 v28, 1, v26
	s_add_u32 s46, s52, s49
	v_cndmask_b32_e64 v27, v26, v27, s[12:13]
	v_fma_f32 v26, -v28, v26, v43
	v_cmp_lt_f32_e64 s[12:13], 0, v26
	s_addc_u32 s47, s53, 0
	s_add_u32 s48, s52, s48
	v_cndmask_b32_e64 v34, v27, v28, s[12:13]
	s_waitcnt lgkmcnt(0)
	v_mfma_f32_32x32x64_f8f6f4 v[18:33], v[18:25], v[146:153], 0
	v_max3_f32 v2, v2, s40, v3
	v_max3_f32 v2, v2, v4, v5
	v_max3_f32 v2, v2, v6, v7
	v_max3_f32 v2, v2, v8, v9
	v_mul_f32_e32 v35, 0x37800000, v34
	v_max3_f32 v2, v2, v10, v11
	v_cndmask_b32_e32 v44, v34, v35, vcc
	ds_read_b128 v[34:37], v171 offset:4096
	ds_read_b128 v[38:41], v171 offset:5120
	v_max3_f32 v2, v2, v12, v13
	v_max3_f32 v2, v2, v14, v15
	v_max3_f32 v2, v2, v16, v17
	v_cmp_lt_i32_e32 vcc, v176, v177
	s_addc_u32 s49, s53, 0
	s_add_u32 s52, s52, s55
	s_addc_u32 s53, s53, 0
	s_nop 3
	v_max3_f32 v2, v2, v18, v19
	v_max3_f32 v2, v2, v20, v21
	v_max3_f32 v18, v2, v22, v23
	s_waitcnt lgkmcnt(0)
	v_mfma_f32_32x32x64_f8f6f4 v[2:17], v[34:41], v[146:153], 0
	v_max3_f32 v18, v18, v24, v25
	v_max3_f32 v18, v18, v26, v27
	v_max3_f32 v18, v18, v28, v29
	v_max3_f32 v18, v18, v30, v31
	v_max3_f32 v26, v18, v32, v33
	ds_read_b128 v[18:21], v171 offset:6144
	ds_read_b128 v[22:25], v171 offset:7168
	s_mov_b32 s65, 0
	s_mov_b32 s55, 0
	v_mov_b32_e32 v27, v163
	v_mov_b32_e32 v28, v163
	v_mov_b32_e32 v29, v163
	v_mov_b32_e32 v30, v163
	v_mov_b32_e32 v31, v163
	v_mov_b32_e32 v32, v163
	v_mov_b32_e32 v33, v163
	s_nop 3
	v_max3_f32 v2, v26, v2, v3
	v_max3_f32 v2, v2, v4, v5
	v_max3_f32 v2, v2, v6, v7
	v_max3_f32 v2, v2, v8, v9
	v_max3_f32 v2, v2, v10, v11
	v_max3_f32 v2, v2, v12, v13
	v_max3_f32 v2, v2, v14, v15
	v_max3_f32 v26, v2, v16, v17
	s_waitcnt lgkmcnt(0)
	v_mfma_f32_32x32x64_f8f6f4 v[2:17], v[18:25], v[146:153], 0
	v_mov_b32_e32 v18, 0
	v_mov_b32_e32 v19, v163
	v_mov_b32_e32 v20, v163
	v_mov_b32_e32 v21, v163
	v_mov_b32_e32 v22, v163
	v_mov_b32_e32 v23, v163
	v_mov_b32_e32 v24, v163
	v_mov_b32_e32 v25, v163
	v_mov_b32_e32 v34, 0
	v_mov_b32_e32 v35, v163
	v_mov_b32_e32 v36, v163
	v_mov_b32_e32 v37, v163
	v_mov_b32_e32 v38, v163
	v_mov_b32_e32 v39, v163
	v_mov_b32_e32 v40, v163
	s_nop 4
	v_max3_f32 v2, v26, v2, v3
	v_max3_f32 v2, v2, v4, v5
	v_max3_f32 v2, v2, v6, v7
	v_max3_f32 v2, v2, v8, v9
	v_max3_f32 v2, v2, v10, v11
	v_max3_f32 v2, v2, v12, v13
	v_max3_f32 v2, v2, v14, v15
	v_cndmask_b32_e32 v3, v175, v176, vcc
	v_max3_f32 v2, v2, v16, v17
	v_lshlrev_b32_e32 v3, 2, v3
	ds_bpermute_b32 v3, v3, v2
	v_cmp_class_f32_e32 vcc, v43, v172
	v_mov_b32_e32 v5, v163
	v_mov_b32_e32 v6, v163
	v_cndmask_b32_e32 v4, v44, v43, vcc
	s_waitcnt lgkmcnt(0)
	v_max_f32_e32 v3, v3, v3
	v_mul_f32_e32 v4, v42, v4
	v_max_f32_e32 v2, v2, v3
	v_fmamk_f32 v4, v4, 0x3f90a3d7, v173
	v_add_f32_e32 v2, 0x42800000, v2
	v_min_f32_e32 v2, v4, v2
	v_add_f32_e32 v2, 0xc2ec0000, v2
	v_xor_b32_e32 v50, 0x80000000, v2
	v_mov_b32_e32 v51, v50
	v_mov_b32_e32 v52, v50
	v_mov_b32_e32 v53, v50
	v_mov_b32_e32 v54, v50
	v_mov_b32_e32 v55, v50
	v_mov_b32_e32 v56, v50
	v_mov_b32_e32 v57, v50
	v_mov_b32_e32 v58, v50
	v_mov_b32_e32 v59, v50
	v_mov_b32_e32 v60, v50
	v_mov_b32_e32 v61, v50
	v_mov_b32_e32 v62, v50
	v_mov_b32_e32 v63, v50
	v_mov_b32_e32 v64, v50
	v_mov_b32_e32 v65, v50
	v_mov_b32_e32 v2, 0
	v_mov_b32_e32 v3, v163
	v_mov_b32_e32 v4, v163
	v_mov_b32_e32 v7, v163
	v_mov_b32_e32 v8, v163
	v_mov_b32_e32 v9, v163
	v_mov_b32_e32 v10, v163
	v_mov_b32_e32 v11, v163
	v_mov_b32_e32 v12, v163
	v_mov_b32_e32 v13, v163
	v_mov_b32_e32 v14, v163
	v_mov_b32_e32 v15, v163
	v_mov_b32_e32 v16, v163
	v_mov_b32_e32 v17, v163
	v_mov_b32_e32 v26, v163
	v_mov_b32_e32 v41, v163
	v_mov_b32_e32 v42, v163
	v_mov_b32_e32 v43, v163
	v_mov_b32_e32 v44, v163
	v_mov_b32_e32 v45, v163
	v_mov_b32_e32 v46, v163
	v_mov_b32_e32 v47, v163
	v_mov_b32_e32 v48, v163
	v_mov_b32_e32 v49, v163
	v_mov_b32_e32 v66, 0
	v_mov_b32_e32 v67, v163
	v_mov_b32_e32 v68, v163
	v_mov_b32_e32 v69, v163
	v_mov_b32_e32 v70, v163
	v_mov_b32_e32 v71, v163
	v_mov_b32_e32 v72, v163
	v_mov_b32_e32 v73, v163
	v_mov_b32_e32 v74, v163
	v_mov_b32_e32 v75, v163
	v_mov_b32_e32 v76, v163
	v_mov_b32_e32 v77, v163
	v_mov_b32_e32 v78, v163
	v_mov_b32_e32 v79, v163
	v_mov_b32_e32 v80, v163
	v_mov_b32_e32 v81, v163
	v_mov_b32_e32 v82, 0
	v_mov_b32_e32 v83, v163
	v_mov_b32_e32 v84, v163
	v_mov_b32_e32 v85, v163
	v_mov_b32_e32 v86, v163
	v_mov_b32_e32 v87, v163
	v_mov_b32_e32 v88, v163
	v_mov_b32_e32 v89, v163
	v_mov_b32_e32 v90, v163
	v_mov_b32_e32 v91, v163
	v_mov_b32_e32 v92, v163
	v_mov_b32_e32 v93, v163
	v_mov_b32_e32 v94, v163
	v_mov_b32_e32 v95, v163
	v_mov_b32_e32 v96, v163
	v_mov_b32_e32 v97, v163
	v_mov_b32_e32 v142, v210
	v_mov_b32_e32 v143, v211
	v_mov_b32_e32 v144, v218
	v_mov_b32_e32 v145, v219
	v_mov_b32_e32 v118, v163
	v_mov_b32_e32 v119, v163
	v_mov_b32_e32 v120, v163
	v_mov_b32_e32 v121, v163
	v_mov_b32_e32 v122, v163
	v_mov_b32_e32 v123, v163
	v_mov_b32_e32 v124, v163
	v_mov_b32_e32 v125, v163
	v_mov_b32_e32 v126, v163
	v_mov_b32_e32 v127, v163
	v_mov_b32_e32 v128, v163
	v_mov_b32_e32 v129, v163
	v_mov_b32_e32 v130, v163
	v_mov_b32_e32 v131, v163
	v_mov_b32_e32 v132, v163
	v_mov_b32_e32 v133, v163
	v_mov_b32_e32 v180, v163
	v_mov_b32_e32 v181, v163
	v_mov_b32_e32 v182, v163
	v_mov_b32_e32 v183, v163
	v_mov_b32_e32 v184, v163
	v_mov_b32_e32 v185, v163
	v_mov_b32_e32 v186, v163
	v_mov_b32_e32 v187, v163
	v_mov_b32_e32 v188, v163
	v_mov_b32_e32 v189, v163
	v_mov_b32_e32 v190, v163
	v_mov_b32_e32 v191, v163
	v_mov_b32_e32 v192, v163
	v_mov_b32_e32 v193, v163
	v_mov_b32_e32 v194, v163
	v_mov_b32_e32 v195, v163
	v_mov_b32_e32 v220, v163
	v_mov_b32_e32 v221, v163
	v_mov_b32_e32 v222, v163
	v_mov_b32_e32 v223, v163
	v_mov_b32_e32 v224, v163
	v_mov_b32_e32 v225, v163
	v_mov_b32_e32 v226, v163
	v_mov_b32_e32 v227, v163
	v_mov_b32_e32 v228, v163
	v_mov_b32_e32 v229, v163
	v_mov_b32_e32 v230, v163
	v_mov_b32_e32 v231, v163
	v_mov_b32_e32 v232, v163
	v_mov_b32_e32 v233, v163
	v_mov_b32_e32 v234, v163
	v_mov_b32_e32 v235, v163
	v_mov_b32_e32 v236, v163
	v_mov_b32_e32 v237, v163
	v_mov_b32_e32 v238, v163
	v_mov_b32_e32 v239, v163
	v_mov_b32_e32 v240, v163
	v_mov_b32_e32 v241, v163
	v_mov_b32_e32 v242, v163
	v_mov_b32_e32 v243, v163
	v_mov_b32_e32 v244, v163
	v_mov_b32_e32 v245, v163
	v_mov_b32_e32 v246, v163
	v_mov_b32_e32 v247, v163
	v_mov_b32_e32 v248, v163
	v_mov_b32_e32 v249, v163
	v_mov_b32_e32 v250, v163
	v_mov_b32_e32 v251, v163
	s_add_u32 s98, s29, s44
	s_addc_u32 s99, s30, s45
	s_add_u32 s98, s98, 0x36532100
	s_addc_u32 s99, s99, 0
	s_add_u32 s100, s29, s52
	s_addc_u32 s101, s30, s53
	s_add_u32 s100, s100, 0x385b6100
	s_addc_u32 s101, s101, 0
	s_movk_i32 s2, 0x4000
	s_and_b64 s[0:1], s[14:15], exec
	s_cselect_b32 s1, s99, s101
	s_cselect_b32 s0, s98, s100
	s_cselect_b32 s2, 0x2000, s2
	s_add_u32 s8, s0, s2
	s_addc_u32 s9, s1, 0
	s_lshl_b32 s2, s2, 1
	s_add_u32 s98, s29, s44
	s_addc_u32 s99, s30, s45
	s_add_u32 s98, s98, 0x36532500
	s_addc_u32 s99, s99, 0
	s_add_u32 s100, s29, s48
	s_addc_u32 s101, s30, s49
	s_add_u32 s100, s100, 0x385b6100
	s_addc_u32 s101, s101, 0
	s_movk_i32 s33, 0x4000
	s_and_b64 s[4:5], s[14:15], exec
	s_cselect_b32 s5, s99, s101
	s_cselect_b32 s4, s98, s100
	s_cselect_b32 s33, 0x2000, s33
	s_add_u32 s10, s4, s33
	s_addc_u32 s11, s5, 0
	s_lshl_b32 s33, s33, 1
	s_add_u32 s98, s29, s44
	s_addc_u32 s99, s30, s45
	s_add_u32 s98, s98, 0x36532900
	s_addc_u32 s99, s99, 0
	s_add_u32 s100, s29, s46
	s_addc_u32 s101, s30, s47
	s_add_u32 s100, s100, 0x385b6100
	s_addc_u32 s101, s101, 0
	s_movk_i32 s50, 0x4000
	s_and_b64 s[6:7], s[26:27], exec
	s_cselect_b32 s7, s99, s101
	s_cselect_b32 s6, s98, s100
	s_cselect_b32 s50, 0x2000, s50
	s_add_u32 s66, s6, s50
	s_addc_u32 s67, s7, 0
	s_lshl_b32 s50, s50, 1
	s_mov_b64 s[98:99], 0
	v_mov_b32_e32 v179, v171
	v_add_u32_e32 v135, 0xc000, v171
	s_waitcnt vmcnt(0) lgkmcnt(0)
	s_barrier
	ds_read_b128 v[204:207], v179
	ds_read_b128 v[208:211], v179 offset:1024
	ds_read_b128 v[212:215], v179 offset:2048
	ds_read_b128 v[216:219], v179 offset:3072
	s_waitcnt lgkmcnt(0)
	s_branch .LBB0_4071

.LBB0_4071:
	s_cmpk_gt_u32 s55, 0x7f
	s_cselect_b64 vcc, 0, exec
	s_add_i32 s55, s55, 2
	s_xor_b32 s65, s65, 2
	s_cmp_lg_u64 s[98:99], 0
	s_cbranch_scc1 .Lslow_dif1_0
.Lback_dif1_0:
	v_cvt_pk_u8_f32 v196, v118, 0, 0
	v_cvt_pk_u8_f32 v197, v122, 0, 0
	v_cvt_pk_u8_f32 v198, v126, 0, 0
	v_cvt_pk_u8_f32 v199, v130, 0, 0
	v_cvt_pk_u8_f32 v196, v119, 1, v196
	v_cvt_pk_u8_f32 v197, v123, 1, v197
	v_cvt_pk_u8_f32 v198, v127, 1, v198
	v_cvt_pk_u8_f32 v199, v131, 1, v199
	s_waitcnt lgkmcnt(10)
	v_mfma_f32_32x32x64_f8f6f4 v[86:101], v[204:211], v[146:153], v[50:65]
	v_cvt_pk_u8_f32 v196, v120, 2, v196
	v_cvt_pk_u8_f32 v197, v124, 2, v197
	v_cvt_pk_u8_f32 v198, v128, 2, v198
	v_cvt_pk_u8_f32 v199, v132, 2, v199
	v_cvt_pk_u8_f32 v196, v121, 3, v196
	v_cvt_pk_u8_f32 v197, v125, 3, v197
	v_cvt_pk_u8_f32 v198, v129, 3, v198
	v_cvt_pk_u8_f32 v199, v133, 3, v199
	v_cvt_pk_u8_f32 v200, v180, 0, 0
	v_cvt_pk_u8_f32 v201, v184, 0, 0
	v_cvt_pk_u8_f32 v202, v188, 0, 0
	v_cvt_pk_u8_f32 v203, v192, 0, 0
	s_waitcnt lgkmcnt(8)
	v_mfma_f32_32x32x64_f8f6f4 v[102:117], v[212:219], v[146:153], v[50:65]
	v_cvt_pk_u8_f32 v200, v181, 1, v200
	v_cvt_pk_u8_f32 v201, v185, 1, v201
	v_cvt_pk_u8_f32 v202, v189, 1, v202
	v_cvt_pk_u8_f32 v203, v193, 1, v203
	v_cvt_pk_u8_f32 v200, v182, 2, v200
	v_cvt_pk_u8_f32 v201, v186, 2, v201
	v_cvt_pk_u8_f32 v202, v190, 2, v202
	v_cvt_pk_u8_f32 v203, v194, 2, v203
	v_cvt_pk_u8_f32 v200, v183, 3, v200
	v_cvt_pk_u8_f32 v201, v187, 3, v201
	v_cvt_pk_u8_f32 v202, v191, 3, v202
	v_cvt_pk_u8_f32 v203, v195, 3, v203
	s_nop 0
	s_waitcnt lgkmcnt(0)
	s_barrier
	v_mfma_f32_32x32x64_f8f6f4 v[66:81], v[220:227], v[196:203], v[66:81] blgp:1
	ds_read_b128 v[204:207], v179 offset:4096
	ds_read_b128 v[208:211], v179 offset:5120
	ds_read_b128 v[212:215], v179 offset:6144
	ds_read_b128 v[216:219], v179 offset:7168
	s_cbranch_vccz .Ldma_dif1_skip0
	s_mul_i32 s101, s65, 0x6000
	s_add_i32 s101, s101, s24
	s_mov_b32 m0, s101
	s_nop 0
	global_load_lds_dwordx4 v164, s[0:1]
